# combo21 + GEMM K-loops: counter update and exit test moved in front of the trip's closing barrier (back edge = barrier + branch)
# baseline (speedup 1.0000x reference)
.Lmy_rs0_wd:
	s_waitcnt lgkmcnt(0)
	s_barrier
	s_setprio 1
	s_waitcnt lgkmcnt(0)
	v_mfma_f32_16x16x32_bf16 v[124:127], v[154:157], v[188:191], v[124:127]
	v_mfma_f32_16x16x32_bf16 v[120:123], v[162:165], v[188:191], v[120:123]
	v_mfma_f32_16x16x32_bf16 v[116:119], v[154:157], v[196:199], v[116:119]
	v_mfma_f32_16x16x32_bf16 v[112:115], v[162:165], v[196:199], v[112:115]
	v_mfma_f32_16x16x32_bf16 v[108:111], v[154:157], v[204:207], v[108:111]
	v_mfma_f32_16x16x32_bf16 v[100:103], v[162:165], v[204:207], v[100:103]
	v_mfma_f32_16x16x32_bf16 v[76:79], v[154:157], v[212:215], v[76:79]
	v_mfma_f32_16x16x32_bf16 v[72:75], v[162:165], v[212:215], v[72:75]
	v_mfma_f32_16x16x32_bf16 v[124:127], v[158:161], v[192:195], v[124:127]
	v_mfma_f32_16x16x32_bf16 v[120:123], v[166:169], v[192:195], v[120:123]
	v_mfma_f32_16x16x32_bf16 v[116:119], v[158:161], v[200:203], v[116:119]
	v_mfma_f32_16x16x32_bf16 v[112:115], v[166:169], v[200:203], v[112:115]
	v_mfma_f32_16x16x32_bf16 v[108:111], v[158:161], v[208:211], v[108:111]
	v_mfma_f32_16x16x32_bf16 v[100:103], v[166:169], v[208:211], v[100:103]
	v_mfma_f32_16x16x32_bf16 v[76:79], v[158:161], v[216:219], v[76:79]
	v_mfma_f32_16x16x32_bf16 v[72:75], v[166:169], v[216:219], v[72:75]
	s_setprio 0
	s_setprio 1
	v_mfma_f32_16x16x32_bf16 v[104:107], v[172:175], v[188:191], v[104:107]
	v_mfma_f32_16x16x32_bf16 v[96:99], v[180:183], v[188:191], v[96:99]
	v_mfma_f32_16x16x32_bf16 v[92:95], v[172:175], v[196:199], v[92:95]
	v_mfma_f32_16x16x32_bf16 v[88:91], v[180:183], v[196:199], v[88:91]
	v_mfma_f32_16x16x32_bf16 v[84:87], v[172:175], v[204:207], v[84:87]
	v_mfma_f32_16x16x32_bf16 v[80:83], v[180:183], v[204:207], v[80:83]
	v_mfma_f32_16x16x32_bf16 v[68:71], v[172:175], v[212:215], v[68:71]
	v_mfma_f32_16x16x32_bf16 v[64:67], v[180:183], v[212:215], v[64:67]
	v_mfma_f32_16x16x32_bf16 v[104:107], v[176:179], v[192:195], v[104:107]
	v_mfma_f32_16x16x32_bf16 v[96:99], v[184:187], v[192:195], v[96:99]
	v_mfma_f32_16x16x32_bf16 v[92:95], v[176:179], v[200:203], v[92:95]
	v_mfma_f32_16x16x32_bf16 v[88:91], v[184:187], v[200:203], v[88:91]
	v_mfma_f32_16x16x32_bf16 v[84:87], v[176:179], v[208:211], v[84:87]
	v_mfma_f32_16x16x32_bf16 v[80:83], v[184:187], v[208:211], v[80:83]
	v_mfma_f32_16x16x32_bf16 v[68:71], v[176:179], v[216:219], v[68:71]
	v_mfma_f32_16x16x32_bf16 v[64:67], v[184:187], v[216:219], v[64:67]
	s_setprio 0
	s_barrier
	s_add_i32 s38, s67, s43
	v_lshl_add_u64 v[220:221], v[220:221], 0, s[8:9]
	s_mov_b32 m0, s38
	ds_read_b128 v[188:191], v152 offset:49152
	ds_read_b128 v[192:195], v152 offset:50176
	ds_read_b128 v[196:199], v152 offset:51200
	ds_read_b128 v[200:203], v152 offset:52224
	ds_read_b128 v[204:207], v152 offset:53248
	ds_read_b128 v[208:211], v152 offset:54272
	ds_read_b128 v[212:215], v152 offset:55296
	ds_read_b128 v[216:219], v152 offset:56320
	global_load_lds_dwordx4 v[220:221], off
	s_add_i32 m0, s38, 0x2000
	s_add_u32 s36, s36, 0x40080
	v_lshl_add_u64 v[220:221], v[222:223], 0, s[8:9]
	s_addc_u32 s37, s37, 0
	s_add_i32 s38, s68, s43
	global_load_lds_dwordx4 v[220:221], off
	v_lshl_add_u64 v[220:221], s[36:37], 0, v[132:133]
	s_mov_b32 m0, s38
	s_nop 0
	global_load_lds_dwordx4 v[220:221], off
	v_lshl_add_u64 v[220:221], s[36:37], 0, v[128:129]
	s_add_i32 m0, s38, 0x2000
	s_nop 0
	global_load_lds_dwordx4 v[220:221], off
	v_lshl_add_u64 v[220:221], v[224:225], 0, s[8:9]
	s_mov_b32 m0, s50
	s_nop 0
	global_load_lds_dwordx4 v[220:221], off
	v_lshl_add_u64 v[220:221], v[226:227], 0, s[8:9]
	s_mov_b32 m0, s51
	s_nop 0
	global_load_lds_dwordx4 v[220:221], off
	s_waitcnt vmcnt(8)
	s_waitcnt lgkmcnt(0)
	s_barrier
	s_setprio 1
	s_waitcnt lgkmcnt(0)
	v_mfma_f32_16x16x32_bf16 v[60:63], v[154:157], v[188:191], v[60:63]
	v_mfma_f32_16x16x32_bf16 v[56:59], v[162:165], v[188:191], v[56:59]
	v_mfma_f32_16x16x32_bf16 v[52:55], v[154:157], v[196:199], v[52:55]
	v_mfma_f32_16x16x32_bf16 v[44:47], v[162:165], v[196:199], v[44:47]
	v_mfma_f32_16x16x32_bf16 v[36:39], v[154:157], v[204:207], v[36:39]
	v_mfma_f32_16x16x32_bf16 v[28:31], v[162:165], v[204:207], v[28:31]
	v_mfma_f32_16x16x32_bf16 v[20:23], v[154:157], v[212:215], v[20:23]
	v_mfma_f32_16x16x32_bf16 v[12:15], v[162:165], v[212:215], v[12:15]
	v_mfma_f32_16x16x32_bf16 v[60:63], v[158:161], v[192:195], v[60:63]
	v_mfma_f32_16x16x32_bf16 v[56:59], v[166:169], v[192:195], v[56:59]
	v_mfma_f32_16x16x32_bf16 v[52:55], v[158:161], v[200:203], v[52:55]
	v_mfma_f32_16x16x32_bf16 v[44:47], v[166:169], v[200:203], v[44:47]
	v_mfma_f32_16x16x32_bf16 v[36:39], v[158:161], v[208:211], v[36:39]
	v_mfma_f32_16x16x32_bf16 v[28:31], v[166:169], v[208:211], v[28:31]
	v_mfma_f32_16x16x32_bf16 v[20:23], v[158:161], v[216:219], v[20:23]
	v_mfma_f32_16x16x32_bf16 v[12:15], v[166:169], v[216:219], v[12:15]
	s_setprio 0
	s_setprio 1
	v_mfma_f32_16x16x32_bf16 v[48:51], v[172:175], v[188:191], v[48:51]
	v_mfma_f32_16x16x32_bf16 v[40:43], v[180:183], v[188:191], v[40:43]
	v_mfma_f32_16x16x32_bf16 v[32:35], v[172:175], v[196:199], v[32:35]
	v_mfma_f32_16x16x32_bf16 v[24:27], v[180:183], v[196:199], v[24:27]
	v_mfma_f32_16x16x32_bf16 v[16:19], v[172:175], v[204:207], v[16:19]
	v_mfma_f32_16x16x32_bf16 v[8:11], v[180:183], v[204:207], v[8:11]
	v_mfma_f32_16x16x32_bf16 v[4:7], v[172:175], v[212:215], v[4:7]
	v_mfma_f32_16x16x32_bf16 v[0:3], v[180:183], v[212:215], v[0:3]
	v_mfma_f32_16x16x32_bf16 v[48:51], v[176:179], v[192:195], v[48:51]
	v_mfma_f32_16x16x32_bf16 v[40:43], v[184:187], v[192:195], v[40:43]
	v_mfma_f32_16x16x32_bf16 v[32:35], v[176:179], v[200:203], v[32:35]
	v_mfma_f32_16x16x32_bf16 v[24:27], v[184:187], v[200:203], v[24:27]
	v_mfma_f32_16x16x32_bf16 v[16:19], v[176:179], v[208:211], v[16:19]
	v_mfma_f32_16x16x32_bf16 v[8:11], v[184:187], v[208:211], v[8:11]
	v_mfma_f32_16x16x32_bf16 v[4:7], v[176:179], v[216:219], v[4:7]
	v_mfma_f32_16x16x32_bf16 v[0:3], v[184:187], v[216:219], v[0:3]
	s_setprio 0
	s_add_i32 s66, s66, 2
	s_add_u32 s34, s34, 0x100
	s_addc_u32 s35, s35, 0
	s_add_u32 s64, s64, 0x100
	s_addc_u32 s65, s65, 0
	s_cmp_gt_u32 s66, 13
	s_barrier
	s_cbranch_scc0 .LBB0_236
	s_and_b64 vcc, exec, s[10:11]
	s_cbranch_vccz .LBB0_239
	s_barrier

.Lmy_rs5_wd:
	s_waitcnt lgkmcnt(0)
	s_barrier
	s_setprio 1
	s_waitcnt lgkmcnt(0)
	v_mfma_f32_16x16x32_bf16 v[124:127], v[146:149], v[188:191], v[124:127]
	v_mfma_f32_16x16x32_bf16 v[120:123], v[154:157], v[188:191], v[120:123]
	v_mfma_f32_16x16x32_bf16 v[108:111], v[146:149], v[196:199], v[108:111]
	v_mfma_f32_16x16x32_bf16 v[104:107], v[154:157], v[196:199], v[104:107]
	v_mfma_f32_16x16x32_bf16 v[92:95], v[146:149], v[204:207], v[92:95]
	v_mfma_f32_16x16x32_bf16 v[88:91], v[154:157], v[204:207], v[88:91]
	v_mfma_f32_16x16x32_bf16 v[76:79], v[146:149], v[212:215], v[76:79]
	v_mfma_f32_16x16x32_bf16 v[72:75], v[154:157], v[212:215], v[72:75]
	v_mfma_f32_16x16x32_bf16 v[124:127], v[150:153], v[192:195], v[124:127]
	v_mfma_f32_16x16x32_bf16 v[120:123], v[158:161], v[192:195], v[120:123]
	v_mfma_f32_16x16x32_bf16 v[108:111], v[150:153], v[200:203], v[108:111]
	v_mfma_f32_16x16x32_bf16 v[104:107], v[158:161], v[200:203], v[104:107]
	v_mfma_f32_16x16x32_bf16 v[92:95], v[150:153], v[208:211], v[92:95]
	v_mfma_f32_16x16x32_bf16 v[88:91], v[158:161], v[208:211], v[88:91]
	v_mfma_f32_16x16x32_bf16 v[76:79], v[150:153], v[216:219], v[76:79]
	v_mfma_f32_16x16x32_bf16 v[72:75], v[158:161], v[216:219], v[72:75]
	s_setprio 0
	s_setprio 1
	v_mfma_f32_16x16x32_bf16 v[116:119], v[172:175], v[188:191], v[116:119]
	v_mfma_f32_16x16x32_bf16 v[112:115], v[180:183], v[188:191], v[112:115]
	v_mfma_f32_16x16x32_bf16 v[100:103], v[172:175], v[196:199], v[100:103]
	v_mfma_f32_16x16x32_bf16 v[96:99], v[180:183], v[196:199], v[96:99]
	v_mfma_f32_16x16x32_bf16 v[84:87], v[172:175], v[204:207], v[84:87]
	v_mfma_f32_16x16x32_bf16 v[80:83], v[180:183], v[204:207], v[80:83]
	v_mfma_f32_16x16x32_bf16 v[68:71], v[172:175], v[212:215], v[68:71]
	v_mfma_f32_16x16x32_bf16 v[64:67], v[180:183], v[212:215], v[64:67]
	v_mfma_f32_16x16x32_bf16 v[116:119], v[176:179], v[192:195], v[116:119]
	v_mfma_f32_16x16x32_bf16 v[112:115], v[184:187], v[192:195], v[112:115]
	v_mfma_f32_16x16x32_bf16 v[100:103], v[176:179], v[200:203], v[100:103]
	v_mfma_f32_16x16x32_bf16 v[96:99], v[184:187], v[200:203], v[96:99]
	v_mfma_f32_16x16x32_bf16 v[84:87], v[176:179], v[208:211], v[84:87]
	v_mfma_f32_16x16x32_bf16 v[80:83], v[184:187], v[208:211], v[80:83]
	v_mfma_f32_16x16x32_bf16 v[68:71], v[176:179], v[216:219], v[68:71]
	v_mfma_f32_16x16x32_bf16 v[64:67], v[184:187], v[216:219], v[64:67]
	s_setprio 0
	s_barrier
	s_add_i32 s50, s74, s57
	v_lshl_add_u64 v[162:163], v[162:163], 0, s[18:19]
	s_mov_b32 m0, s50
	ds_read_b128 v[188:191], v169 offset:49152
	ds_read_b128 v[192:195], v169 offset:50176
	ds_read_b128 v[196:199], v169 offset:51200
	ds_read_b128 v[200:203], v169 offset:52224
	ds_read_b128 v[204:207], v169 offset:53248
	ds_read_b128 v[208:211], v169 offset:54272
	ds_read_b128 v[212:215], v169 offset:55296
	ds_read_b128 v[216:219], v169 offset:56320
	global_load_lds_dwordx4 v[162:163], off
	s_add_i32 m0, s50, 0x2000
	s_add_u32 s48, s48, 0x40080
	v_lshl_add_u64 v[162:163], v[220:221], 0, s[18:19]
	s_addc_u32 s49, s49, 0
	s_add_i32 s50, s75, s57
	global_load_lds_dwordx4 v[162:163], off
	v_lshl_add_u64 v[162:163], s[48:49], 0, v[130:131]
	s_mov_b32 m0, s50
	s_nop 0
	global_load_lds_dwordx4 v[162:163], off
	v_lshl_add_u64 v[162:163], s[48:49], 0, v[134:135]
	s_add_i32 m0, s50, 0x2000
	s_nop 0
	global_load_lds_dwordx4 v[162:163], off
	v_lshl_add_u64 v[162:163], v[222:223], 0, s[18:19]
	s_mov_b32 m0, s33
	s_nop 0
	global_load_lds_dwordx4 v[162:163], off
	v_lshl_add_u64 v[162:163], v[224:225], 0, s[18:19]
	s_mov_b32 m0, s62
	s_nop 0
	global_load_lds_dwordx4 v[162:163], off
	s_waitcnt vmcnt(8)
	s_waitcnt lgkmcnt(0)
	s_barrier
	s_setprio 1
	s_waitcnt lgkmcnt(0)
	v_mfma_f32_16x16x32_bf16 v[60:63], v[146:149], v[188:191], v[60:63]
	v_mfma_f32_16x16x32_bf16 v[56:59], v[154:157], v[188:191], v[56:59]
	v_mfma_f32_16x16x32_bf16 v[44:47], v[146:149], v[196:199], v[44:47]
	v_mfma_f32_16x16x32_bf16 v[40:43], v[154:157], v[196:199], v[40:43]
	v_mfma_f32_16x16x32_bf16 v[28:31], v[146:149], v[204:207], v[28:31]
	v_mfma_f32_16x16x32_bf16 v[24:27], v[154:157], v[204:207], v[24:27]
	v_mfma_f32_16x16x32_bf16 v[12:15], v[146:149], v[212:215], v[12:15]
	v_mfma_f32_16x16x32_bf16 v[8:11], v[154:157], v[212:215], v[8:11]
	v_mfma_f32_16x16x32_bf16 v[60:63], v[150:153], v[192:195], v[60:63]
	v_mfma_f32_16x16x32_bf16 v[56:59], v[158:161], v[192:195], v[56:59]
	v_mfma_f32_16x16x32_bf16 v[44:47], v[150:153], v[200:203], v[44:47]
	v_mfma_f32_16x16x32_bf16 v[40:43], v[158:161], v[200:203], v[40:43]
	v_mfma_f32_16x16x32_bf16 v[28:31], v[150:153], v[208:211], v[28:31]
	v_mfma_f32_16x16x32_bf16 v[24:27], v[158:161], v[208:211], v[24:27]
	v_mfma_f32_16x16x32_bf16 v[12:15], v[150:153], v[216:219], v[12:15]
	v_mfma_f32_16x16x32_bf16 v[8:11], v[158:161], v[216:219], v[8:11]
	s_setprio 0
	s_setprio 1
	v_mfma_f32_16x16x32_bf16 v[52:55], v[172:175], v[188:191], v[52:55]
	v_mfma_f32_16x16x32_bf16 v[48:51], v[180:183], v[188:191], v[48:51]
	v_mfma_f32_16x16x32_bf16 v[36:39], v[172:175], v[196:199], v[36:39]
	v_mfma_f32_16x16x32_bf16 v[32:35], v[180:183], v[196:199], v[32:35]
	v_mfma_f32_16x16x32_bf16 v[20:23], v[172:175], v[204:207], v[20:23]
	v_mfma_f32_16x16x32_bf16 v[16:19], v[180:183], v[204:207], v[16:19]
	v_mfma_f32_16x16x32_bf16 v[4:7], v[172:175], v[212:215], v[4:7]
	v_mfma_f32_16x16x32_bf16 v[0:3], v[180:183], v[212:215], v[0:3]
	v_mfma_f32_16x16x32_bf16 v[52:55], v[176:179], v[192:195], v[52:55]
	v_mfma_f32_16x16x32_bf16 v[48:51], v[184:187], v[192:195], v[48:51]
	v_mfma_f32_16x16x32_bf16 v[36:39], v[176:179], v[200:203], v[36:39]
	v_mfma_f32_16x16x32_bf16 v[32:35], v[184:187], v[200:203], v[32:35]
	v_mfma_f32_16x16x32_bf16 v[20:23], v[176:179], v[208:211], v[20:23]
	v_mfma_f32_16x16x32_bf16 v[16:19], v[184:187], v[208:211], v[16:19]
	v_mfma_f32_16x16x32_bf16 v[4:7], v[176:179], v[216:219], v[4:7]
	v_mfma_f32_16x16x32_bf16 v[0:3], v[184:187], v[216:219], v[0:3]
	s_setprio 0
	s_add_i32 s73, s73, 2
	s_add_u32 s46, s46, 0x100
	s_addc_u32 s47, s47, 0
	s_add_u32 s53, s53, 0x100
	s_addc_u32 s72, s72, 0
	s_cmp_gt_u32 s73, 13
	s_barrier
	s_cbranch_scc0 .LBB0_445
	s_and_b64 vcc, exec, s[20:21]
	s_cbranch_vccz .LBB0_448
	s_barrier

.Lmy_rs8_wd:
	s_waitcnt lgkmcnt(0)
	s_barrier
	s_setprio 1
	s_waitcnt lgkmcnt(0)
	v_mfma_f32_16x16x32_bf16 v[124:127], v[144:147], v[186:189], v[124:127]
	v_mfma_f32_16x16x32_bf16 v[120:123], v[152:155], v[186:189], v[120:123]
	v_mfma_f32_16x16x32_bf16 v[108:111], v[144:147], v[194:197], v[108:111]
	v_mfma_f32_16x16x32_bf16 v[104:107], v[152:155], v[194:197], v[104:107]
	v_mfma_f32_16x16x32_bf16 v[92:95], v[144:147], v[202:205], v[92:95]
	v_mfma_f32_16x16x32_bf16 v[88:91], v[152:155], v[202:205], v[88:91]
	v_mfma_f32_16x16x32_bf16 v[76:79], v[144:147], v[210:213], v[76:79]
	v_mfma_f32_16x16x32_bf16 v[72:75], v[152:155], v[210:213], v[72:75]
	v_mfma_f32_16x16x32_bf16 v[124:127], v[148:151], v[190:193], v[124:127]
	v_mfma_f32_16x16x32_bf16 v[120:123], v[156:159], v[190:193], v[120:123]
	v_mfma_f32_16x16x32_bf16 v[108:111], v[148:151], v[198:201], v[108:111]
	v_mfma_f32_16x16x32_bf16 v[104:107], v[156:159], v[198:201], v[104:107]
	v_mfma_f32_16x16x32_bf16 v[92:95], v[148:151], v[206:209], v[92:95]
	v_mfma_f32_16x16x32_bf16 v[88:91], v[156:159], v[206:209], v[88:91]
	v_mfma_f32_16x16x32_bf16 v[76:79], v[148:151], v[214:217], v[76:79]
	v_mfma_f32_16x16x32_bf16 v[72:75], v[156:159], v[214:217], v[72:75]
	s_setprio 0
	s_setprio 1
	v_mfma_f32_16x16x32_bf16 v[116:119], v[160:163], v[186:189], v[116:119]
	v_mfma_f32_16x16x32_bf16 v[112:115], v[178:181], v[186:189], v[112:115]
	v_mfma_f32_16x16x32_bf16 v[100:103], v[160:163], v[194:197], v[100:103]
	v_mfma_f32_16x16x32_bf16 v[96:99], v[178:181], v[194:197], v[96:99]
	v_mfma_f32_16x16x32_bf16 v[84:87], v[160:163], v[202:205], v[84:87]
	v_mfma_f32_16x16x32_bf16 v[80:83], v[178:181], v[202:205], v[80:83]
	v_mfma_f32_16x16x32_bf16 v[68:71], v[160:163], v[210:213], v[68:71]
	v_mfma_f32_16x16x32_bf16 v[64:67], v[178:181], v[210:213], v[64:67]
	v_mfma_f32_16x16x32_bf16 v[116:119], v[164:167], v[190:193], v[116:119]
	v_mfma_f32_16x16x32_bf16 v[112:115], v[182:185], v[190:193], v[112:115]
	v_mfma_f32_16x16x32_bf16 v[100:103], v[164:167], v[198:201], v[100:103]
	v_mfma_f32_16x16x32_bf16 v[96:99], v[182:185], v[198:201], v[96:99]
	v_mfma_f32_16x16x32_bf16 v[84:87], v[164:167], v[206:209], v[84:87]
	v_mfma_f32_16x16x32_bf16 v[80:83], v[182:185], v[206:209], v[80:83]
	v_mfma_f32_16x16x32_bf16 v[68:71], v[164:167], v[214:217], v[68:71]
	v_mfma_f32_16x16x32_bf16 v[64:67], v[182:185], v[214:217], v[64:67]
	s_setprio 0
	s_barrier
	s_add_i32 s50, s72, s55
	v_lshl_add_u64 v[168:169], v[168:169], 0, s[16:17]
	s_mov_b32 m0, s50
	ds_read_b128 v[186:189], v176 offset:49152
	ds_read_b128 v[190:193], v176 offset:50176
	ds_read_b128 v[194:197], v176 offset:51200
	ds_read_b128 v[198:201], v176 offset:52224
	ds_read_b128 v[202:205], v176 offset:53248
	ds_read_b128 v[206:209], v176 offset:54272
	ds_read_b128 v[210:213], v176 offset:55296
	ds_read_b128 v[214:217], v176 offset:56320
	global_load_lds_dwordx4 v[168:169], off
	s_add_i32 m0, s50, 0x2000
	s_add_u32 s48, s48, 0x40080
	v_lshl_add_u64 v[168:169], v[218:219], 0, s[16:17]
	s_addc_u32 s49, s49, 0
	s_add_i32 s50, s73, s55
	global_load_lds_dwordx4 v[168:169], off
	v_lshl_add_u64 v[168:169], s[48:49], 0, v[130:131]
	s_mov_b32 m0, s50
	s_nop 0
	global_load_lds_dwordx4 v[168:169], off
	v_lshl_add_u64 v[168:169], s[48:49], 0, v[134:135]
	s_add_i32 m0, s50, 0x2000
	s_nop 0
	global_load_lds_dwordx4 v[168:169], off
	v_lshl_add_u64 v[168:169], v[220:221], 0, s[16:17]
	s_mov_b32 m0, s61
	s_nop 0
	global_load_lds_dwordx4 v[168:169], off
	v_lshl_add_u64 v[168:169], v[222:223], 0, s[16:17]
	s_mov_b32 m0, s62
	s_nop 0
	global_load_lds_dwordx4 v[168:169], off
	s_waitcnt vmcnt(8)
	s_waitcnt lgkmcnt(0)
	s_barrier
	s_setprio 1
	s_waitcnt lgkmcnt(0)
	v_mfma_f32_16x16x32_bf16 v[60:63], v[144:147], v[186:189], v[60:63]
	v_mfma_f32_16x16x32_bf16 v[56:59], v[152:155], v[186:189], v[56:59]
	v_mfma_f32_16x16x32_bf16 v[44:47], v[144:147], v[194:197], v[44:47]
	v_mfma_f32_16x16x32_bf16 v[40:43], v[152:155], v[194:197], v[40:43]
	v_mfma_f32_16x16x32_bf16 v[28:31], v[144:147], v[202:205], v[28:31]
	v_mfma_f32_16x16x32_bf16 v[24:27], v[152:155], v[202:205], v[24:27]
	v_mfma_f32_16x16x32_bf16 v[12:15], v[144:147], v[210:213], v[12:15]
	v_mfma_f32_16x16x32_bf16 v[8:11], v[152:155], v[210:213], v[8:11]
	v_mfma_f32_16x16x32_bf16 v[60:63], v[148:151], v[190:193], v[60:63]
	v_mfma_f32_16x16x32_bf16 v[56:59], v[156:159], v[190:193], v[56:59]
	v_mfma_f32_16x16x32_bf16 v[44:47], v[148:151], v[198:201], v[44:47]
	v_mfma_f32_16x16x32_bf16 v[40:43], v[156:159], v[198:201], v[40:43]
	v_mfma_f32_16x16x32_bf16 v[28:31], v[148:151], v[206:209], v[28:31]
	v_mfma_f32_16x16x32_bf16 v[24:27], v[156:159], v[206:209], v[24:27]
	v_mfma_f32_16x16x32_bf16 v[12:15], v[148:151], v[214:217], v[12:15]
	v_mfma_f32_16x16x32_bf16 v[8:11], v[156:159], v[214:217], v[8:11]
	s_setprio 0
	s_setprio 1
	v_mfma_f32_16x16x32_bf16 v[52:55], v[160:163], v[186:189], v[52:55]
	v_mfma_f32_16x16x32_bf16 v[48:51], v[178:181], v[186:189], v[48:51]
	v_mfma_f32_16x16x32_bf16 v[36:39], v[160:163], v[194:197], v[36:39]
	v_mfma_f32_16x16x32_bf16 v[32:35], v[178:181], v[194:197], v[32:35]
	v_mfma_f32_16x16x32_bf16 v[20:23], v[160:163], v[202:205], v[20:23]
	v_mfma_f32_16x16x32_bf16 v[16:19], v[178:181], v[202:205], v[16:19]
	v_mfma_f32_16x16x32_bf16 v[4:7], v[160:163], v[210:213], v[4:7]
	v_mfma_f32_16x16x32_bf16 v[0:3], v[178:181], v[210:213], v[0:3]
	v_mfma_f32_16x16x32_bf16 v[52:55], v[164:167], v[190:193], v[52:55]
	v_mfma_f32_16x16x32_bf16 v[48:51], v[182:185], v[190:193], v[48:51]
	v_mfma_f32_16x16x32_bf16 v[36:39], v[164:167], v[198:201], v[36:39]
	v_mfma_f32_16x16x32_bf16 v[32:35], v[182:185], v[198:201], v[32:35]
	v_mfma_f32_16x16x32_bf16 v[20:23], v[164:167], v[206:209], v[20:23]
	v_mfma_f32_16x16x32_bf16 v[16:19], v[182:185], v[206:209], v[16:19]
	v_mfma_f32_16x16x32_bf16 v[4:7], v[164:167], v[214:217], v[4:7]
	v_mfma_f32_16x16x32_bf16 v[0:3], v[182:185], v[214:217], v[0:3]
	s_setprio 0
	s_add_i32 s71, s71, 2
	s_add_u32 s46, s46, 0x100
	s_addc_u32 s47, s47, 0
	s_add_u32 s41, s41, 0x100
	s_addc_u32 s70, s70, 0
	s_cmp_gt_u32 s71, 13
	s_barrier
	s_cbranch_scc0 .LBB0_771
	s_and_b64 vcc, exec, s[18:19]
	s_cbranch_vccz .LBB0_774
	s_barrier

.LBB0_1033:
	ds_read_b128 v[144:147], v151
	ds_read_b128 v[162:165], v151 offset:1024
	ds_read_b128 v[166:169], v151 offset:2048
	ds_read_b128 v[172:175], v151 offset:3072
	ds_read_b128 v[176:179], v160
	ds_read_b128 v[180:183], v160 offset:1024
	ds_read_b128 v[184:187], v160 offset:2048
	ds_read_b128 v[188:191], v160 offset:3072
	s_add_u32 s42, s40, 0xfffc0080
	s_addc_u32 s43, s41, -1
	s_cmp_eq_u32 s65, 12
	s_cselect_b32 s45, s1, s43
	s_cselect_b32 s44, s35, s42
	s_cselect_b32 s43, s27, s64
	s_cselect_b32 s42, s62, s63
	v_lshl_add_u64 v[224:225], s[40:41], 0, v[136:137]
	s_add_i32 m0, s11, 0xc000
	ds_read_b128 v[192:195], v161
	ds_read_b128 v[196:199], v161 offset:1024
	ds_read_b128 v[200:203], v161 offset:2048
	ds_read_b128 v[204:207], v161 offset:3072
	ds_read_b128 v[208:211], v161 offset:4096
	ds_read_b128 v[212:215], v161 offset:5120
	ds_read_b128 v[216:219], v161 offset:6144
	ds_read_b128 v[220:223], v161 offset:7168
	global_load_lds_dwordx4 v[224:225], off
	v_lshl_add_u64 v[224:225], s[40:41], 0, v[138:139]
	s_add_i32 m0, s11, 0xe000
	s_nop 0
	global_load_lds_dwordx4 v[224:225], off
	s_waitcnt vmcnt(8)
	s_waitcnt lgkmcnt(0)
	s_barrier
	s_setprio 1
	s_waitcnt lgkmcnt(0)
	v_mfma_f32_16x16x32_bf16 v[124:127], v[144:147], v[192:195], v[124:127]
	v_mfma_f32_16x16x32_bf16 v[120:123], v[166:169], v[192:195], v[120:123]
	v_mfma_f32_16x16x32_bf16 v[108:111], v[144:147], v[200:203], v[108:111]
	v_mfma_f32_16x16x32_bf16 v[104:107], v[166:169], v[200:203], v[104:107]
	v_mfma_f32_16x16x32_bf16 v[92:95], v[144:147], v[208:211], v[92:95]
	v_mfma_f32_16x16x32_bf16 v[88:91], v[166:169], v[208:211], v[88:91]
	v_mfma_f32_16x16x32_bf16 v[76:79], v[144:147], v[216:219], v[76:79]
	v_mfma_f32_16x16x32_bf16 v[72:75], v[166:169], v[216:219], v[72:75]
	v_mfma_f32_16x16x32_bf16 v[124:127], v[162:165], v[196:199], v[124:127]
	v_mfma_f32_16x16x32_bf16 v[120:123], v[172:175], v[196:199], v[120:123]
	v_mfma_f32_16x16x32_bf16 v[108:111], v[162:165], v[204:207], v[108:111]
	v_mfma_f32_16x16x32_bf16 v[104:107], v[172:175], v[204:207], v[104:107]
	v_mfma_f32_16x16x32_bf16 v[92:95], v[162:165], v[212:215], v[92:95]
	v_mfma_f32_16x16x32_bf16 v[88:91], v[172:175], v[212:215], v[88:91]
	v_mfma_f32_16x16x32_bf16 v[76:79], v[162:165], v[220:223], v[76:79]
	v_mfma_f32_16x16x32_bf16 v[72:75], v[172:175], v[220:223], v[72:75]
	s_setprio 0
	s_setprio 1
	v_mfma_f32_16x16x32_bf16 v[116:119], v[176:179], v[192:195], v[116:119]
	v_mfma_f32_16x16x32_bf16 v[112:115], v[184:187], v[192:195], v[112:115]
	v_mfma_f32_16x16x32_bf16 v[100:103], v[176:179], v[200:203], v[100:103]
	v_mfma_f32_16x16x32_bf16 v[96:99], v[184:187], v[200:203], v[96:99]
	v_mfma_f32_16x16x32_bf16 v[84:87], v[176:179], v[208:211], v[84:87]
	v_mfma_f32_16x16x32_bf16 v[80:83], v[184:187], v[208:211], v[80:83]
	v_mfma_f32_16x16x32_bf16 v[68:71], v[176:179], v[216:219], v[68:71]
	v_mfma_f32_16x16x32_bf16 v[64:67], v[184:187], v[216:219], v[64:67]
	v_mfma_f32_16x16x32_bf16 v[116:119], v[180:183], v[196:199], v[116:119]
	v_mfma_f32_16x16x32_bf16 v[112:115], v[188:191], v[196:199], v[112:115]
	v_mfma_f32_16x16x32_bf16 v[100:103], v[180:183], v[204:207], v[100:103]
	v_mfma_f32_16x16x32_bf16 v[96:99], v[188:191], v[204:207], v[96:99]
	v_mfma_f32_16x16x32_bf16 v[84:87], v[180:183], v[212:215], v[84:87]
	v_mfma_f32_16x16x32_bf16 v[80:83], v[188:191], v[212:215], v[80:83]
	v_mfma_f32_16x16x32_bf16 v[68:71], v[180:183], v[220:223], v[68:71]
	v_mfma_f32_16x16x32_bf16 v[64:67], v[188:191], v[220:223], v[64:67]
	s_setprio 0
	s_barrier
	s_add_i32 s66, s60, s47
	v_lshl_add_u64 v[224:225], s[42:43], 0, v[130:131]
	s_mov_b32 m0, s66
	ds_read_b128 v[192:195], v161 offset:16384
	ds_read_b128 v[196:199], v161 offset:17408
	ds_read_b128 v[200:203], v161 offset:18432
	ds_read_b128 v[204:207], v161 offset:19456
	ds_read_b128 v[208:211], v161 offset:20480
	ds_read_b128 v[212:215], v161 offset:21504
	ds_read_b128 v[216:219], v161 offset:22528
	ds_read_b128 v[220:223], v161 offset:23552
	global_load_lds_dwordx4 v[224:225], off
	s_add_i32 m0, s66, 0x2000
	s_add_u32 s66, s42, 0x40000
	v_lshl_add_u64 v[226:227], s[42:43], 0, v[134:135]
	s_addc_u32 s67, s43, 0
	s_add_i32 s68, s61, s47
	global_load_lds_dwordx4 v[226:227], off
	v_lshl_add_u64 v[228:229], s[66:67], 0, v[130:131]
	s_mov_b32 m0, s68
	v_lshl_add_u64 v[230:231], s[44:45], 0, v[132:133]
	global_load_lds_dwordx4 v[228:229], off
	v_lshl_add_u64 v[228:229], s[66:67], 0, v[134:135]
	s_add_i32 m0, s68, 0x2000
	s_nop 0
	global_load_lds_dwordx4 v[228:229], off
	v_lshl_add_u64 v[228:229], s[44:45], 0, v[128:129]
	s_mov_b32 m0, s11
	s_nop 0
	global_load_lds_dwordx4 v[228:229], off
	s_mov_b32 m0, s48
	s_nop 0
	global_load_lds_dwordx4 v[230:231], off
	s_waitcnt vmcnt(8)
	s_waitcnt lgkmcnt(0)
	s_barrier
	s_setprio 1
	s_waitcnt lgkmcnt(0)
	v_mfma_f32_16x16x32_bf16 v[60:63], v[144:147], v[192:195], v[60:63]
	v_mfma_f32_16x16x32_bf16 v[56:59], v[166:169], v[192:195], v[56:59]
	v_mfma_f32_16x16x32_bf16 v[44:47], v[144:147], v[200:203], v[44:47]
	v_mfma_f32_16x16x32_bf16 v[40:43], v[166:169], v[200:203], v[40:43]
	v_mfma_f32_16x16x32_bf16 v[28:31], v[144:147], v[208:211], v[28:31]
	v_mfma_f32_16x16x32_bf16 v[24:27], v[166:169], v[208:211], v[24:27]
	v_mfma_f32_16x16x32_bf16 v[12:15], v[144:147], v[216:219], v[12:15]
	v_mfma_f32_16x16x32_bf16 v[8:11], v[166:169], v[216:219], v[8:11]
	v_mfma_f32_16x16x32_bf16 v[60:63], v[162:165], v[196:199], v[60:63]
	v_mfma_f32_16x16x32_bf16 v[56:59], v[172:175], v[196:199], v[56:59]
	v_mfma_f32_16x16x32_bf16 v[44:47], v[162:165], v[204:207], v[44:47]
	v_mfma_f32_16x16x32_bf16 v[40:43], v[172:175], v[204:207], v[40:43]
	v_mfma_f32_16x16x32_bf16 v[28:31], v[162:165], v[212:215], v[28:31]
	v_mfma_f32_16x16x32_bf16 v[24:27], v[172:175], v[212:215], v[24:27]
	v_mfma_f32_16x16x32_bf16 v[12:15], v[162:165], v[220:223], v[12:15]
	v_mfma_f32_16x16x32_bf16 v[8:11], v[172:175], v[220:223], v[8:11]
	s_setprio 0
	s_setprio 1
	v_mfma_f32_16x16x32_bf16 v[52:55], v[176:179], v[192:195], v[52:55]
	v_mfma_f32_16x16x32_bf16 v[48:51], v[184:187], v[192:195], v[48:51]
	v_mfma_f32_16x16x32_bf16 v[36:39], v[176:179], v[200:203], v[36:39]
	v_mfma_f32_16x16x32_bf16 v[32:35], v[184:187], v[200:203], v[32:35]
	v_mfma_f32_16x16x32_bf16 v[20:23], v[176:179], v[208:211], v[20:23]
	v_mfma_f32_16x16x32_bf16 v[16:19], v[184:187], v[208:211], v[16:19]
	v_mfma_f32_16x16x32_bf16 v[4:7], v[176:179], v[216:219], v[4:7]
	v_mfma_f32_16x16x32_bf16 v[0:3], v[184:187], v[216:219], v[0:3]
	v_mfma_f32_16x16x32_bf16 v[52:55], v[180:183], v[196:199], v[52:55]
	v_mfma_f32_16x16x32_bf16 v[48:51], v[188:191], v[196:199], v[48:51]
	v_mfma_f32_16x16x32_bf16 v[36:39], v[180:183], v[204:207], v[36:39]
	v_mfma_f32_16x16x32_bf16 v[32:35], v[188:191], v[204:207], v[32:35]
	v_mfma_f32_16x16x32_bf16 v[20:23], v[180:183], v[212:215], v[20:23]
	v_mfma_f32_16x16x32_bf16 v[16:19], v[188:191], v[212:215], v[16:19]
	v_mfma_f32_16x16x32_bf16 v[4:7], v[180:183], v[220:223], v[4:7]
	v_mfma_f32_16x16x32_bf16 v[0:3], v[188:191], v[220:223], v[0:3]
	s_setprio 0
	s_barrier
	s_add_i32 s66, 0, 0x18000
	v_add_u32_e32 v171, s66, v149
	s_add_i32 s67, 0, 0x1c000
	ds_read_b128 v[144:147], v171
	ds_read_b128 v[162:165], v171 offset:1024
	ds_read_b128 v[166:169], v171 offset:2048
	ds_read_b128 v[172:175], v171 offset:3072
	v_add_u32_e32 v171, s67, v149
	ds_read_b128 v[176:179], v171
	ds_read_b128 v[180:183], v171 offset:1024
	ds_read_b128 v[184:187], v171 offset:2048
	ds_read_b128 v[188:191], v171 offset:3072
	s_add_u32 s44, s44, 0x40000
	s_addc_u32 s45, s45, 0
	s_mov_b32 m0, s49
	v_lshl_add_u64 v[232:233], s[44:45], 0, v[128:129]
	ds_read_b128 v[192:195], v161 offset:32768
	ds_read_b128 v[196:199], v161 offset:33792
	ds_read_b128 v[200:203], v161 offset:34816
	ds_read_b128 v[204:207], v161 offset:35840
	ds_read_b128 v[208:211], v161 offset:36864
	ds_read_b128 v[212:215], v161 offset:37888
	ds_read_b128 v[216:219], v161 offset:38912
	ds_read_b128 v[220:223], v161 offset:39936
	global_load_lds_dwordx4 v[232:233], off
	v_lshl_add_u64 v[232:233], s[44:45], 0, v[132:133]
	s_mov_b32 m0, s51
	s_nop 0
	global_load_lds_dwordx4 v[232:233], off
	s_waitcnt vmcnt(8)
	s_waitcnt lgkmcnt(0)
	s_barrier
	s_setprio 1
	s_waitcnt lgkmcnt(0)
	v_mfma_f32_16x16x32_bf16 v[124:127], v[144:147], v[192:195], v[124:127]
	v_mfma_f32_16x16x32_bf16 v[120:123], v[166:169], v[192:195], v[120:123]
	v_mfma_f32_16x16x32_bf16 v[108:111], v[144:147], v[200:203], v[108:111]
	v_mfma_f32_16x16x32_bf16 v[104:107], v[166:169], v[200:203], v[104:107]
	v_mfma_f32_16x16x32_bf16 v[92:95], v[144:147], v[208:211], v[92:95]
	v_mfma_f32_16x16x32_bf16 v[88:91], v[166:169], v[208:211], v[88:91]
	v_mfma_f32_16x16x32_bf16 v[76:79], v[144:147], v[216:219], v[76:79]
	v_mfma_f32_16x16x32_bf16 v[72:75], v[166:169], v[216:219], v[72:75]
	v_mfma_f32_16x16x32_bf16 v[124:127], v[162:165], v[196:199], v[124:127]
	v_mfma_f32_16x16x32_bf16 v[120:123], v[172:175], v[196:199], v[120:123]
	v_mfma_f32_16x16x32_bf16 v[108:111], v[162:165], v[204:207], v[108:111]
	v_mfma_f32_16x16x32_bf16 v[104:107], v[172:175], v[204:207], v[104:107]
	v_mfma_f32_16x16x32_bf16 v[92:95], v[162:165], v[212:215], v[92:95]
	v_mfma_f32_16x16x32_bf16 v[88:91], v[172:175], v[212:215], v[88:91]
	v_mfma_f32_16x16x32_bf16 v[76:79], v[162:165], v[220:223], v[76:79]
	v_mfma_f32_16x16x32_bf16 v[72:75], v[172:175], v[220:223], v[72:75]
	s_setprio 0
	s_setprio 1
	v_mfma_f32_16x16x32_bf16 v[116:119], v[176:179], v[192:195], v[116:119]
	v_mfma_f32_16x16x32_bf16 v[112:115], v[184:187], v[192:195], v[112:115]
	v_mfma_f32_16x16x32_bf16 v[100:103], v[176:179], v[200:203], v[100:103]
	v_mfma_f32_16x16x32_bf16 v[96:99], v[184:187], v[200:203], v[96:99]
	v_mfma_f32_16x16x32_bf16 v[84:87], v[176:179], v[208:211], v[84:87]
	v_mfma_f32_16x16x32_bf16 v[80:83], v[184:187], v[208:211], v[80:83]
	v_mfma_f32_16x16x32_bf16 v[68:71], v[176:179], v[216:219], v[68:71]
	v_mfma_f32_16x16x32_bf16 v[64:67], v[184:187], v[216:219], v[64:67]
	v_mfma_f32_16x16x32_bf16 v[116:119], v[180:183], v[196:199], v[116:119]
	v_mfma_f32_16x16x32_bf16 v[112:115], v[188:191], v[196:199], v[112:115]
	v_mfma_f32_16x16x32_bf16 v[100:103], v[180:183], v[204:207], v[100:103]
	v_mfma_f32_16x16x32_bf16 v[96:99], v[188:191], v[204:207], v[96:99]
	v_mfma_f32_16x16x32_bf16 v[84:87], v[180:183], v[212:215], v[84:87]
	v_mfma_f32_16x16x32_bf16 v[80:83], v[188:191], v[212:215], v[80:83]
	v_mfma_f32_16x16x32_bf16 v[68:71], v[180:183], v[220:223], v[68:71]
	v_mfma_f32_16x16x32_bf16 v[64:67], v[188:191], v[220:223], v[64:67]
	s_setprio 0
	s_barrier
	s_add_i32 s44, s66, s47
	v_lshl_add_u64 v[224:225], v[224:225], 0, s[14:15]
	s_mov_b32 m0, s44
	ds_read_b128 v[192:195], v161 offset:49152
	ds_read_b128 v[196:199], v161 offset:50176
	ds_read_b128 v[200:203], v161 offset:51200
	ds_read_b128 v[204:207], v161 offset:52224
	ds_read_b128 v[208:211], v161 offset:53248
	ds_read_b128 v[212:215], v161 offset:54272
	ds_read_b128 v[216:219], v161 offset:55296
	ds_read_b128 v[220:223], v161 offset:56320
	global_load_lds_dwordx4 v[224:225], off
	s_add_i32 m0, s44, 0x2000
	s_add_u32 s42, s42, 0x40080
	v_lshl_add_u64 v[224:225], v[226:227], 0, s[14:15]
	s_addc_u32 s43, s43, 0
	s_add_i32 s44, s67, s47
	global_load_lds_dwordx4 v[224:225], off
	v_lshl_add_u64 v[224:225], s[42:43], 0, v[130:131]
	s_mov_b32 m0, s44
	s_nop 0
	global_load_lds_dwordx4 v[224:225], off
	v_lshl_add_u64 v[224:225], s[42:43], 0, v[134:135]
	s_add_i32 m0, s44, 0x2000
	s_nop 0
	global_load_lds_dwordx4 v[224:225], off
	v_lshl_add_u64 v[224:225], v[228:229], 0, s[14:15]
	s_mov_b32 m0, s53
	s_nop 0
	global_load_lds_dwordx4 v[224:225], off
	v_lshl_add_u64 v[224:225], v[230:231], 0, s[14:15]
	s_mov_b32 m0, s54
	s_nop 0
	global_load_lds_dwordx4 v[224:225], off
	s_waitcnt vmcnt(8)
	s_waitcnt lgkmcnt(0)
	s_barrier
	s_setprio 1
	s_waitcnt lgkmcnt(0)
	v_mfma_f32_16x16x32_bf16 v[60:63], v[144:147], v[192:195], v[60:63]
	v_mfma_f32_16x16x32_bf16 v[56:59], v[166:169], v[192:195], v[56:59]
	v_mfma_f32_16x16x32_bf16 v[44:47], v[144:147], v[200:203], v[44:47]
	v_mfma_f32_16x16x32_bf16 v[40:43], v[166:169], v[200:203], v[40:43]
	v_mfma_f32_16x16x32_bf16 v[28:31], v[144:147], v[208:211], v[28:31]
	v_mfma_f32_16x16x32_bf16 v[24:27], v[166:169], v[208:211], v[24:27]
	v_mfma_f32_16x16x32_bf16 v[12:15], v[144:147], v[216:219], v[12:15]
	v_mfma_f32_16x16x32_bf16 v[8:11], v[166:169], v[216:219], v[8:11]
	v_mfma_f32_16x16x32_bf16 v[60:63], v[162:165], v[196:199], v[60:63]
	v_mfma_f32_16x16x32_bf16 v[56:59], v[172:175], v[196:199], v[56:59]
	v_mfma_f32_16x16x32_bf16 v[44:47], v[162:165], v[204:207], v[44:47]
	v_mfma_f32_16x16x32_bf16 v[40:43], v[172:175], v[204:207], v[40:43]
	v_mfma_f32_16x16x32_bf16 v[28:31], v[162:165], v[212:215], v[28:31]
	v_mfma_f32_16x16x32_bf16 v[24:27], v[172:175], v[212:215], v[24:27]
	v_mfma_f32_16x16x32_bf16 v[12:15], v[162:165], v[220:223], v[12:15]
	v_mfma_f32_16x16x32_bf16 v[8:11], v[172:175], v[220:223], v[8:11]
	s_setprio 0
	s_setprio 1
	v_mfma_f32_16x16x32_bf16 v[52:55], v[176:179], v[192:195], v[52:55]
	v_mfma_f32_16x16x32_bf16 v[48:51], v[184:187], v[192:195], v[48:51]
	v_mfma_f32_16x16x32_bf16 v[36:39], v[176:179], v[200:203], v[36:39]
	v_mfma_f32_16x16x32_bf16 v[32:35], v[184:187], v[200:203], v[32:35]
	v_mfma_f32_16x16x32_bf16 v[20:23], v[176:179], v[208:211], v[20:23]
	v_mfma_f32_16x16x32_bf16 v[16:19], v[184:187], v[208:211], v[16:19]
	v_mfma_f32_16x16x32_bf16 v[4:7], v[176:179], v[216:219], v[4:7]
	v_mfma_f32_16x16x32_bf16 v[0:3], v[184:187], v[216:219], v[0:3]
	v_mfma_f32_16x16x32_bf16 v[52:55], v[180:183], v[196:199], v[52:55]
	v_mfma_f32_16x16x32_bf16 v[48:51], v[188:191], v[196:199], v[48:51]
	v_mfma_f32_16x16x32_bf16 v[36:39], v[180:183], v[204:207], v[36:39]
	v_mfma_f32_16x16x32_bf16 v[32:35], v[188:191], v[204:207], v[32:35]
	v_mfma_f32_16x16x32_bf16 v[20:23], v[180:183], v[212:215], v[20:23]
	v_mfma_f32_16x16x32_bf16 v[16:19], v[188:191], v[212:215], v[16:19]
	v_mfma_f32_16x16x32_bf16 v[4:7], v[180:183], v[220:223], v[4:7]
	v_mfma_f32_16x16x32_bf16 v[0:3], v[188:191], v[220:223], v[0:3]
	s_setprio 0
	s_add_i32 s65, s65, 2
	s_add_u32 s40, s40, 0x100
	s_addc_u32 s41, s41, 0
	s_add_u32 s63, s63, 0x100
	s_addc_u32 s64, s64, 0
	s_cmp_gt_u32 s65, 13
	s_barrier
	s_cbranch_scc0 .LBB0_1033
	s_and_b64 vcc, exec, s[16:17]
	s_cbranch_vccz .LBB0_1036
	s_barrier

.LBB0_1091:
	ds_read_b128 v[144:147], v151
	ds_read_b128 v[162:165], v151 offset:1024
	ds_read_b128 v[166:169], v151 offset:2048
	ds_read_b128 v[172:175], v151 offset:3072
	ds_read_b128 v[176:179], v160
	ds_read_b128 v[180:183], v160 offset:1024
	ds_read_b128 v[184:187], v160 offset:2048
	ds_read_b128 v[188:191], v160 offset:3072
	s_add_u32 s46, s44, 0xfffc0080
	s_addc_u32 s47, s45, -1
	s_cmp_eq_u32 s71, 12
	s_cselect_b32 s49, s1, s47
	s_cselect_b32 s48, s33, s46
	s_cselect_b32 s47, s37, s70
	s_cselect_b32 s46, s39, s69
	v_lshl_add_u64 v[224:225], s[44:45], 0, v[136:137]
	s_add_i32 m0, s21, 0xc000
	ds_read_b128 v[192:195], v161
	ds_read_b128 v[196:199], v161 offset:1024
	ds_read_b128 v[200:203], v161 offset:2048
	ds_read_b128 v[204:207], v161 offset:3072
	ds_read_b128 v[208:211], v161 offset:4096
	ds_read_b128 v[212:215], v161 offset:5120
	ds_read_b128 v[216:219], v161 offset:6144
	ds_read_b128 v[220:223], v161 offset:7168
	global_load_lds_dwordx4 v[224:225], off
	v_lshl_add_u64 v[224:225], s[44:45], 0, v[138:139]
	s_add_i32 m0, s21, 0xe000
	s_nop 0
	global_load_lds_dwordx4 v[224:225], off
	s_waitcnt vmcnt(8)
	s_waitcnt lgkmcnt(0)
	s_barrier
	s_setprio 1
	s_waitcnt lgkmcnt(0)
	v_mfma_f32_16x16x32_bf16 v[124:127], v[144:147], v[192:195], v[124:127]
	v_mfma_f32_16x16x32_bf16 v[120:123], v[166:169], v[192:195], v[120:123]
	v_mfma_f32_16x16x32_bf16 v[108:111], v[144:147], v[200:203], v[108:111]
	v_mfma_f32_16x16x32_bf16 v[104:107], v[166:169], v[200:203], v[104:107]
	v_mfma_f32_16x16x32_bf16 v[92:95], v[144:147], v[208:211], v[92:95]
	v_mfma_f32_16x16x32_bf16 v[88:91], v[166:169], v[208:211], v[88:91]
	v_mfma_f32_16x16x32_bf16 v[76:79], v[144:147], v[216:219], v[76:79]
	v_mfma_f32_16x16x32_bf16 v[72:75], v[166:169], v[216:219], v[72:75]
	v_mfma_f32_16x16x32_bf16 v[124:127], v[162:165], v[196:199], v[124:127]
	v_mfma_f32_16x16x32_bf16 v[120:123], v[172:175], v[196:199], v[120:123]
	v_mfma_f32_16x16x32_bf16 v[108:111], v[162:165], v[204:207], v[108:111]
	v_mfma_f32_16x16x32_bf16 v[104:107], v[172:175], v[204:207], v[104:107]
	v_mfma_f32_16x16x32_bf16 v[92:95], v[162:165], v[212:215], v[92:95]
	v_mfma_f32_16x16x32_bf16 v[88:91], v[172:175], v[212:215], v[88:91]
	v_mfma_f32_16x16x32_bf16 v[76:79], v[162:165], v[220:223], v[76:79]
	v_mfma_f32_16x16x32_bf16 v[72:75], v[172:175], v[220:223], v[72:75]
	s_setprio 0
	s_setprio 1
	v_mfma_f32_16x16x32_bf16 v[116:119], v[176:179], v[192:195], v[116:119]
	v_mfma_f32_16x16x32_bf16 v[112:115], v[184:187], v[192:195], v[112:115]
	v_mfma_f32_16x16x32_bf16 v[100:103], v[176:179], v[200:203], v[100:103]
	v_mfma_f32_16x16x32_bf16 v[96:99], v[184:187], v[200:203], v[96:99]
	v_mfma_f32_16x16x32_bf16 v[84:87], v[176:179], v[208:211], v[84:87]
	v_mfma_f32_16x16x32_bf16 v[80:83], v[184:187], v[208:211], v[80:83]
	v_mfma_f32_16x16x32_bf16 v[68:71], v[176:179], v[216:219], v[68:71]
	v_mfma_f32_16x16x32_bf16 v[64:67], v[184:187], v[216:219], v[64:67]
	v_mfma_f32_16x16x32_bf16 v[116:119], v[180:183], v[196:199], v[116:119]
	v_mfma_f32_16x16x32_bf16 v[112:115], v[188:191], v[196:199], v[112:115]
	v_mfma_f32_16x16x32_bf16 v[100:103], v[180:183], v[204:207], v[100:103]
	v_mfma_f32_16x16x32_bf16 v[96:99], v[188:191], v[204:207], v[96:99]
	v_mfma_f32_16x16x32_bf16 v[84:87], v[180:183], v[212:215], v[84:87]
	v_mfma_f32_16x16x32_bf16 v[80:83], v[188:191], v[212:215], v[80:83]
	v_mfma_f32_16x16x32_bf16 v[68:71], v[180:183], v[220:223], v[68:71]
	v_mfma_f32_16x16x32_bf16 v[64:67], v[188:191], v[220:223], v[64:67]
	s_setprio 0
	s_barrier
	s_add_i32 s72, s67, s55
	v_lshl_add_u64 v[224:225], s[46:47], 0, v[130:131]
	s_mov_b32 m0, s72
	ds_read_b128 v[192:195], v161 offset:16384
	ds_read_b128 v[196:199], v161 offset:17408
	ds_read_b128 v[200:203], v161 offset:18432
	ds_read_b128 v[204:207], v161 offset:19456
	ds_read_b128 v[208:211], v161 offset:20480
	ds_read_b128 v[212:215], v161 offset:21504
	ds_read_b128 v[216:219], v161 offset:22528
	ds_read_b128 v[220:223], v161 offset:23552
	global_load_lds_dwordx4 v[224:225], off
	s_add_i32 m0, s72, 0x2000
	s_add_u32 s72, s46, 0x40000
	v_lshl_add_u64 v[226:227], s[46:47], 0, v[134:135]
	s_addc_u32 s73, s47, 0
	s_add_i32 s74, s68, s55
	global_load_lds_dwordx4 v[226:227], off
	v_lshl_add_u64 v[228:229], s[72:73], 0, v[130:131]
	s_mov_b32 m0, s74
	v_lshl_add_u64 v[230:231], s[48:49], 0, v[132:133]
	global_load_lds_dwordx4 v[228:229], off
	v_lshl_add_u64 v[228:229], s[72:73], 0, v[134:135]
	s_add_i32 m0, s74, 0x2000
	s_nop 0
	global_load_lds_dwordx4 v[228:229], off
	v_lshl_add_u64 v[228:229], s[48:49], 0, v[128:129]
	s_mov_b32 m0, s21
	s_nop 0
	global_load_lds_dwordx4 v[228:229], off
	s_mov_b32 m0, s56
	s_nop 0
	global_load_lds_dwordx4 v[230:231], off
	s_waitcnt vmcnt(8)
	s_waitcnt lgkmcnt(0)
	s_barrier
	s_setprio 1
	s_waitcnt lgkmcnt(0)
	v_mfma_f32_16x16x32_bf16 v[60:63], v[144:147], v[192:195], v[60:63]
	v_mfma_f32_16x16x32_bf16 v[56:59], v[166:169], v[192:195], v[56:59]
	v_mfma_f32_16x16x32_bf16 v[44:47], v[144:147], v[200:203], v[44:47]
	v_mfma_f32_16x16x32_bf16 v[40:43], v[166:169], v[200:203], v[40:43]
	v_mfma_f32_16x16x32_bf16 v[28:31], v[144:147], v[208:211], v[28:31]
	v_mfma_f32_16x16x32_bf16 v[24:27], v[166:169], v[208:211], v[24:27]
	v_mfma_f32_16x16x32_bf16 v[12:15], v[144:147], v[216:219], v[12:15]
	v_mfma_f32_16x16x32_bf16 v[8:11], v[166:169], v[216:219], v[8:11]
	v_mfma_f32_16x16x32_bf16 v[60:63], v[162:165], v[196:199], v[60:63]
	v_mfma_f32_16x16x32_bf16 v[56:59], v[172:175], v[196:199], v[56:59]
	v_mfma_f32_16x16x32_bf16 v[44:47], v[162:165], v[204:207], v[44:47]
	v_mfma_f32_16x16x32_bf16 v[40:43], v[172:175], v[204:207], v[40:43]
	v_mfma_f32_16x16x32_bf16 v[28:31], v[162:165], v[212:215], v[28:31]
	v_mfma_f32_16x16x32_bf16 v[24:27], v[172:175], v[212:215], v[24:27]
	v_mfma_f32_16x16x32_bf16 v[12:15], v[162:165], v[220:223], v[12:15]
	v_mfma_f32_16x16x32_bf16 v[8:11], v[172:175], v[220:223], v[8:11]
	s_setprio 0
	s_setprio 1
	v_mfma_f32_16x16x32_bf16 v[52:55], v[176:179], v[192:195], v[52:55]
	v_mfma_f32_16x16x32_bf16 v[48:51], v[184:187], v[192:195], v[48:51]
	v_mfma_f32_16x16x32_bf16 v[36:39], v[176:179], v[200:203], v[36:39]
	v_mfma_f32_16x16x32_bf16 v[32:35], v[184:187], v[200:203], v[32:35]
	v_mfma_f32_16x16x32_bf16 v[20:23], v[176:179], v[208:211], v[20:23]
	v_mfma_f32_16x16x32_bf16 v[16:19], v[184:187], v[208:211], v[16:19]
	v_mfma_f32_16x16x32_bf16 v[4:7], v[176:179], v[216:219], v[4:7]
	v_mfma_f32_16x16x32_bf16 v[0:3], v[184:187], v[216:219], v[0:3]
	v_mfma_f32_16x16x32_bf16 v[52:55], v[180:183], v[196:199], v[52:55]
	v_mfma_f32_16x16x32_bf16 v[48:51], v[188:191], v[196:199], v[48:51]
	v_mfma_f32_16x16x32_bf16 v[36:39], v[180:183], v[204:207], v[36:39]
	v_mfma_f32_16x16x32_bf16 v[32:35], v[188:191], v[204:207], v[32:35]
	v_mfma_f32_16x16x32_bf16 v[20:23], v[180:183], v[212:215], v[20:23]
	v_mfma_f32_16x16x32_bf16 v[16:19], v[188:191], v[212:215], v[16:19]
	v_mfma_f32_16x16x32_bf16 v[4:7], v[180:183], v[220:223], v[4:7]
	v_mfma_f32_16x16x32_bf16 v[0:3], v[188:191], v[220:223], v[0:3]
	s_setprio 0
	s_barrier
	s_add_i32 s72, 0, 0x18000
	v_add_u32_e32 v171, s72, v149
	s_add_i32 s73, 0, 0x1c000
	ds_read_b128 v[144:147], v171
	ds_read_b128 v[162:165], v171 offset:1024
	ds_read_b128 v[166:169], v171 offset:2048
	ds_read_b128 v[172:175], v171 offset:3072
	v_add_u32_e32 v171, s73, v149
	ds_read_b128 v[176:179], v171
	ds_read_b128 v[180:183], v171 offset:1024
	ds_read_b128 v[184:187], v171 offset:2048
	ds_read_b128 v[188:191], v171 offset:3072
	s_add_u32 s48, s48, 0x40000
	s_addc_u32 s49, s49, 0
	s_mov_b32 m0, s57
	v_lshl_add_u64 v[232:233], s[48:49], 0, v[128:129]
	ds_read_b128 v[192:195], v161 offset:32768
	ds_read_b128 v[196:199], v161 offset:33792
	ds_read_b128 v[200:203], v161 offset:34816
	ds_read_b128 v[204:207], v161 offset:35840
	ds_read_b128 v[208:211], v161 offset:36864
	ds_read_b128 v[212:215], v161 offset:37888
	ds_read_b128 v[216:219], v161 offset:38912
	ds_read_b128 v[220:223], v161 offset:39936
	global_load_lds_dwordx4 v[232:233], off
	v_lshl_add_u64 v[232:233], s[48:49], 0, v[132:133]
	s_mov_b32 m0, s60
	s_nop 0
	global_load_lds_dwordx4 v[232:233], off
	s_waitcnt vmcnt(8)
	s_waitcnt lgkmcnt(0)
	s_barrier
	s_setprio 1
	s_waitcnt lgkmcnt(0)
	v_mfma_f32_16x16x32_bf16 v[124:127], v[144:147], v[192:195], v[124:127]
	v_mfma_f32_16x16x32_bf16 v[120:123], v[166:169], v[192:195], v[120:123]
	v_mfma_f32_16x16x32_bf16 v[108:111], v[144:147], v[200:203], v[108:111]
	v_mfma_f32_16x16x32_bf16 v[104:107], v[166:169], v[200:203], v[104:107]
	v_mfma_f32_16x16x32_bf16 v[92:95], v[144:147], v[208:211], v[92:95]
	v_mfma_f32_16x16x32_bf16 v[88:91], v[166:169], v[208:211], v[88:91]
	v_mfma_f32_16x16x32_bf16 v[76:79], v[144:147], v[216:219], v[76:79]
	v_mfma_f32_16x16x32_bf16 v[72:75], v[166:169], v[216:219], v[72:75]
	v_mfma_f32_16x16x32_bf16 v[124:127], v[162:165], v[196:199], v[124:127]
	v_mfma_f32_16x16x32_bf16 v[120:123], v[172:175], v[196:199], v[120:123]
	v_mfma_f32_16x16x32_bf16 v[108:111], v[162:165], v[204:207], v[108:111]
	v_mfma_f32_16x16x32_bf16 v[104:107], v[172:175], v[204:207], v[104:107]
	v_mfma_f32_16x16x32_bf16 v[92:95], v[162:165], v[212:215], v[92:95]
	v_mfma_f32_16x16x32_bf16 v[88:91], v[172:175], v[212:215], v[88:91]
	v_mfma_f32_16x16x32_bf16 v[76:79], v[162:165], v[220:223], v[76:79]
	v_mfma_f32_16x16x32_bf16 v[72:75], v[172:175], v[220:223], v[72:75]
	s_setprio 0
	s_setprio 1
	v_mfma_f32_16x16x32_bf16 v[116:119], v[176:179], v[192:195], v[116:119]
	v_mfma_f32_16x16x32_bf16 v[112:115], v[184:187], v[192:195], v[112:115]
	v_mfma_f32_16x16x32_bf16 v[100:103], v[176:179], v[200:203], v[100:103]
	v_mfma_f32_16x16x32_bf16 v[96:99], v[184:187], v[200:203], v[96:99]
	v_mfma_f32_16x16x32_bf16 v[84:87], v[176:179], v[208:211], v[84:87]
	v_mfma_f32_16x16x32_bf16 v[80:83], v[184:187], v[208:211], v[80:83]
	v_mfma_f32_16x16x32_bf16 v[68:71], v[176:179], v[216:219], v[68:71]
	v_mfma_f32_16x16x32_bf16 v[64:67], v[184:187], v[216:219], v[64:67]
	v_mfma_f32_16x16x32_bf16 v[116:119], v[180:183], v[196:199], v[116:119]
	v_mfma_f32_16x16x32_bf16 v[112:115], v[188:191], v[196:199], v[112:115]
	v_mfma_f32_16x16x32_bf16 v[100:103], v[180:183], v[204:207], v[100:103]
	v_mfma_f32_16x16x32_bf16 v[96:99], v[188:191], v[204:207], v[96:99]
	v_mfma_f32_16x16x32_bf16 v[84:87], v[180:183], v[212:215], v[84:87]
	v_mfma_f32_16x16x32_bf16 v[80:83], v[188:191], v[212:215], v[80:83]
	v_mfma_f32_16x16x32_bf16 v[68:71], v[180:183], v[220:223], v[68:71]
	v_mfma_f32_16x16x32_bf16 v[64:67], v[188:191], v[220:223], v[64:67]
	s_setprio 0
	s_barrier
	s_add_i32 s48, s72, s55
	v_lshl_add_u64 v[224:225], v[224:225], 0, s[16:17]
	s_mov_b32 m0, s48
	ds_read_b128 v[192:195], v161 offset:49152
	ds_read_b128 v[196:199], v161 offset:50176
	ds_read_b128 v[200:203], v161 offset:51200
	ds_read_b128 v[204:207], v161 offset:52224
	ds_read_b128 v[208:211], v161 offset:53248
	ds_read_b128 v[212:215], v161 offset:54272
	ds_read_b128 v[216:219], v161 offset:55296
	ds_read_b128 v[220:223], v161 offset:56320
	global_load_lds_dwordx4 v[224:225], off
	s_add_i32 m0, s48, 0x2000
	s_add_u32 s46, s46, 0x40080
	v_lshl_add_u64 v[224:225], v[226:227], 0, s[16:17]
	s_addc_u32 s47, s47, 0
	s_add_i32 s48, s73, s55
	global_load_lds_dwordx4 v[224:225], off
	v_lshl_add_u64 v[224:225], s[46:47], 0, v[130:131]
	s_mov_b32 m0, s48
	s_nop 0
	global_load_lds_dwordx4 v[224:225], off
	v_lshl_add_u64 v[224:225], s[46:47], 0, v[134:135]
	s_add_i32 m0, s48, 0x2000
	s_nop 0
	global_load_lds_dwordx4 v[224:225], off
	v_lshl_add_u64 v[224:225], v[228:229], 0, s[16:17]
	s_mov_b32 m0, s62
	s_nop 0
	global_load_lds_dwordx4 v[224:225], off
	v_lshl_add_u64 v[224:225], v[230:231], 0, s[16:17]
	s_mov_b32 m0, s63
	s_nop 0
	global_load_lds_dwordx4 v[224:225], off
	s_waitcnt vmcnt(8)
	s_waitcnt lgkmcnt(0)
	s_barrier
	s_setprio 1
	s_waitcnt lgkmcnt(0)
	v_mfma_f32_16x16x32_bf16 v[60:63], v[144:147], v[192:195], v[60:63]
	v_mfma_f32_16x16x32_bf16 v[56:59], v[166:169], v[192:195], v[56:59]
	v_mfma_f32_16x16x32_bf16 v[44:47], v[144:147], v[200:203], v[44:47]
	v_mfma_f32_16x16x32_bf16 v[40:43], v[166:169], v[200:203], v[40:43]
	v_mfma_f32_16x16x32_bf16 v[28:31], v[144:147], v[208:211], v[28:31]
	v_mfma_f32_16x16x32_bf16 v[24:27], v[166:169], v[208:211], v[24:27]
	v_mfma_f32_16x16x32_bf16 v[12:15], v[144:147], v[216:219], v[12:15]
	v_mfma_f32_16x16x32_bf16 v[8:11], v[166:169], v[216:219], v[8:11]
	v_mfma_f32_16x16x32_bf16 v[60:63], v[162:165], v[196:199], v[60:63]
	v_mfma_f32_16x16x32_bf16 v[56:59], v[172:175], v[196:199], v[56:59]
	v_mfma_f32_16x16x32_bf16 v[44:47], v[162:165], v[204:207], v[44:47]
	v_mfma_f32_16x16x32_bf16 v[40:43], v[172:175], v[204:207], v[40:43]
	v_mfma_f32_16x16x32_bf16 v[28:31], v[162:165], v[212:215], v[28:31]
	v_mfma_f32_16x16x32_bf16 v[24:27], v[172:175], v[212:215], v[24:27]
	v_mfma_f32_16x16x32_bf16 v[12:15], v[162:165], v[220:223], v[12:15]
	v_mfma_f32_16x16x32_bf16 v[8:11], v[172:175], v[220:223], v[8:11]
	s_setprio 0
	s_setprio 1
	v_mfma_f32_16x16x32_bf16 v[52:55], v[176:179], v[192:195], v[52:55]
	v_mfma_f32_16x16x32_bf16 v[48:51], v[184:187], v[192:195], v[48:51]
	v_mfma_f32_16x16x32_bf16 v[36:39], v[176:179], v[200:203], v[36:39]
	v_mfma_f32_16x16x32_bf16 v[32:35], v[184:187], v[200:203], v[32:35]
	v_mfma_f32_16x16x32_bf16 v[20:23], v[176:179], v[208:211], v[20:23]
	v_mfma_f32_16x16x32_bf16 v[16:19], v[184:187], v[208:211], v[16:19]
	v_mfma_f32_16x16x32_bf16 v[4:7], v[176:179], v[216:219], v[4:7]
	v_mfma_f32_16x16x32_bf16 v[0:3], v[184:187], v[216:219], v[0:3]
	v_mfma_f32_16x16x32_bf16 v[52:55], v[180:183], v[196:199], v[52:55]
	v_mfma_f32_16x16x32_bf16 v[48:51], v[188:191], v[196:199], v[48:51]
	v_mfma_f32_16x16x32_bf16 v[36:39], v[180:183], v[204:207], v[36:39]
	v_mfma_f32_16x16x32_bf16 v[32:35], v[188:191], v[204:207], v[32:35]
	v_mfma_f32_16x16x32_bf16 v[20:23], v[180:183], v[212:215], v[20:23]
	v_mfma_f32_16x16x32_bf16 v[16:19], v[188:191], v[212:215], v[16:19]
	v_mfma_f32_16x16x32_bf16 v[4:7], v[180:183], v[220:223], v[4:7]
	v_mfma_f32_16x16x32_bf16 v[0:3], v[188:191], v[220:223], v[0:3]
	s_setprio 0
	s_add_i32 s71, s71, 2
	s_add_u32 s44, s44, 0x100
	s_addc_u32 s45, s45, 0
	s_add_u32 s69, s69, 0x100
	s_addc_u32 s70, s70, 0
	s_cmp_gt_u32 s71, 13
	s_barrier
	s_cbranch_scc0 .LBB0_1091
	s_and_b64 vcc, exec, s[18:19]
	s_cbranch_vccz .LBB0_1094
	s_barrier

.LBB0_1183:
	ds_read_b128 v[148:151], v164
	ds_read_b128 v[172:175], v164 offset:1024
	ds_read_b128 v[176:179], v164 offset:2048
	ds_read_b128 v[180:183], v164 offset:3072
	ds_read_b128 v[184:187], v165
	ds_read_b128 v[188:191], v165 offset:1024
	ds_read_b128 v[192:195], v165 offset:2048
	ds_read_b128 v[196:199], v165 offset:3072
	s_add_u32 s54, s52, 0xfffc0080
	s_addc_u32 s55, s53, -1
	s_cmp_eq_u32 s77, 12
	s_cselect_b32 s57, s45, s55
	s_cselect_b32 s56, s73, s54
	s_cselect_b32 s55, s43, s76
	s_cselect_b32 s54, s74, s75
	v_lshl_add_u64 v[168:169], s[52:53], 0, v[140:141]
	s_add_i32 m0, s51, 0xc000
	ds_read_b128 v[200:203], v166
	ds_read_b128 v[204:207], v166 offset:1024
	ds_read_b128 v[208:211], v166 offset:2048
	ds_read_b128 v[212:215], v166 offset:3072
	ds_read_b128 v[216:219], v166 offset:4096
	ds_read_b128 v[220:223], v166 offset:5120
	ds_read_b128 v[224:227], v166 offset:6144
	ds_read_b128 v[228:231], v166 offset:7168
	global_load_lds_dwordx4 v[168:169], off
	v_lshl_add_u64 v[168:169], s[52:53], 0, v[142:143]
	s_add_i32 m0, s51, 0xe000
	s_nop 0
	global_load_lds_dwordx4 v[168:169], off
	s_waitcnt vmcnt(8)
	s_waitcnt lgkmcnt(0)
	s_barrier
	s_setprio 1
	s_waitcnt lgkmcnt(0)
	v_mfma_f32_16x16x32_bf16 v[124:127], v[148:151], v[200:203], v[124:127]
	v_mfma_f32_16x16x32_bf16 v[120:123], v[176:179], v[200:203], v[120:123]
	v_mfma_f32_16x16x32_bf16 v[108:111], v[148:151], v[208:211], v[108:111]
	v_mfma_f32_16x16x32_bf16 v[104:107], v[176:179], v[208:211], v[104:107]
	v_mfma_f32_16x16x32_bf16 v[92:95], v[148:151], v[216:219], v[92:95]
	v_mfma_f32_16x16x32_bf16 v[88:91], v[176:179], v[216:219], v[88:91]
	v_mfma_f32_16x16x32_bf16 v[76:79], v[148:151], v[224:227], v[76:79]
	v_mfma_f32_16x16x32_bf16 v[72:75], v[176:179], v[224:227], v[72:75]
	v_mfma_f32_16x16x32_bf16 v[124:127], v[172:175], v[204:207], v[124:127]
	v_mfma_f32_16x16x32_bf16 v[120:123], v[180:183], v[204:207], v[120:123]
	v_mfma_f32_16x16x32_bf16 v[108:111], v[172:175], v[212:215], v[108:111]
	v_mfma_f32_16x16x32_bf16 v[104:107], v[180:183], v[212:215], v[104:107]
	v_mfma_f32_16x16x32_bf16 v[92:95], v[172:175], v[220:223], v[92:95]
	v_mfma_f32_16x16x32_bf16 v[88:91], v[180:183], v[220:223], v[88:91]
	v_mfma_f32_16x16x32_bf16 v[76:79], v[172:175], v[228:231], v[76:79]
	v_mfma_f32_16x16x32_bf16 v[72:75], v[180:183], v[228:231], v[72:75]
	s_setprio 0
	s_setprio 1
	v_mfma_f32_16x16x32_bf16 v[116:119], v[184:187], v[200:203], v[116:119]
	v_mfma_f32_16x16x32_bf16 v[112:115], v[192:195], v[200:203], v[112:115]
	v_mfma_f32_16x16x32_bf16 v[100:103], v[184:187], v[208:211], v[100:103]
	v_mfma_f32_16x16x32_bf16 v[96:99], v[192:195], v[208:211], v[96:99]
	v_mfma_f32_16x16x32_bf16 v[84:87], v[184:187], v[216:219], v[84:87]
	v_mfma_f32_16x16x32_bf16 v[80:83], v[192:195], v[216:219], v[80:83]
	v_mfma_f32_16x16x32_bf16 v[68:71], v[184:187], v[224:227], v[68:71]
	v_mfma_f32_16x16x32_bf16 v[64:67], v[192:195], v[224:227], v[64:67]
	v_mfma_f32_16x16x32_bf16 v[116:119], v[188:191], v[204:207], v[116:119]
	v_mfma_f32_16x16x32_bf16 v[112:115], v[196:199], v[204:207], v[112:115]
	v_mfma_f32_16x16x32_bf16 v[100:103], v[188:191], v[212:215], v[100:103]
	v_mfma_f32_16x16x32_bf16 v[96:99], v[196:199], v[212:215], v[96:99]
	v_mfma_f32_16x16x32_bf16 v[84:87], v[188:191], v[220:223], v[84:87]
	v_mfma_f32_16x16x32_bf16 v[80:83], v[196:199], v[220:223], v[80:83]
	v_mfma_f32_16x16x32_bf16 v[68:71], v[188:191], v[228:231], v[68:71]
	v_mfma_f32_16x16x32_bf16 v[64:67], v[196:199], v[228:231], v[64:67]
	s_setprio 0
	s_barrier
	s_add_i32 s78, s70, s61
	v_lshl_add_u64 v[168:169], s[54:55], 0, v[130:131]
	s_mov_b32 m0, s78
	ds_read_b128 v[200:203], v166 offset:16384
	ds_read_b128 v[204:207], v166 offset:17408
	ds_read_b128 v[208:211], v166 offset:18432
	ds_read_b128 v[212:215], v166 offset:19456
	ds_read_b128 v[216:219], v166 offset:20480
	ds_read_b128 v[220:223], v166 offset:21504
	ds_read_b128 v[224:227], v166 offset:22528
	ds_read_b128 v[228:231], v166 offset:23552
	global_load_lds_dwordx4 v[168:169], off
	s_add_i32 m0, s78, 0x2000
	s_add_u32 s78, s54, 0x40000
	v_lshl_add_u64 v[232:233], s[54:55], 0, v[134:135]
	s_addc_u32 s79, s55, 0
	s_add_i32 s80, s71, s61
	global_load_lds_dwordx4 v[232:233], off
	v_lshl_add_u64 v[234:235], s[78:79], 0, v[130:131]
	s_mov_b32 m0, s80
	v_lshl_add_u64 v[236:237], s[56:57], 0, v[132:133]
	global_load_lds_dwordx4 v[234:235], off
	v_lshl_add_u64 v[234:235], s[78:79], 0, v[134:135]
	s_add_i32 m0, s80, 0x2000
	s_nop 0
	global_load_lds_dwordx4 v[234:235], off
	v_lshl_add_u64 v[234:235], s[56:57], 0, v[128:129]
	s_mov_b32 m0, s51
	s_nop 0
	global_load_lds_dwordx4 v[234:235], off
	s_mov_b32 m0, s62
	s_nop 0
	global_load_lds_dwordx4 v[236:237], off
	s_waitcnt vmcnt(8)
	s_waitcnt lgkmcnt(0)
	s_barrier
	s_setprio 1
	s_waitcnt lgkmcnt(0)
	v_mfma_f32_16x16x32_bf16 v[60:63], v[148:151], v[200:203], v[60:63]
	v_mfma_f32_16x16x32_bf16 v[56:59], v[176:179], v[200:203], v[56:59]
	v_mfma_f32_16x16x32_bf16 v[44:47], v[148:151], v[208:211], v[44:47]
	v_mfma_f32_16x16x32_bf16 v[40:43], v[176:179], v[208:211], v[40:43]
	v_mfma_f32_16x16x32_bf16 v[28:31], v[148:151], v[216:219], v[28:31]
	v_mfma_f32_16x16x32_bf16 v[24:27], v[176:179], v[216:219], v[24:27]
	v_mfma_f32_16x16x32_bf16 v[12:15], v[148:151], v[224:227], v[12:15]
	v_mfma_f32_16x16x32_bf16 v[8:11], v[176:179], v[224:227], v[8:11]
	v_mfma_f32_16x16x32_bf16 v[60:63], v[172:175], v[204:207], v[60:63]
	v_mfma_f32_16x16x32_bf16 v[56:59], v[180:183], v[204:207], v[56:59]
	v_mfma_f32_16x16x32_bf16 v[44:47], v[172:175], v[212:215], v[44:47]
	v_mfma_f32_16x16x32_bf16 v[40:43], v[180:183], v[212:215], v[40:43]
	v_mfma_f32_16x16x32_bf16 v[28:31], v[172:175], v[220:223], v[28:31]
	v_mfma_f32_16x16x32_bf16 v[24:27], v[180:183], v[220:223], v[24:27]
	v_mfma_f32_16x16x32_bf16 v[12:15], v[172:175], v[228:231], v[12:15]
	v_mfma_f32_16x16x32_bf16 v[8:11], v[180:183], v[228:231], v[8:11]
	s_setprio 0
	s_setprio 1
	v_mfma_f32_16x16x32_bf16 v[52:55], v[184:187], v[200:203], v[52:55]
	v_mfma_f32_16x16x32_bf16 v[48:51], v[192:195], v[200:203], v[48:51]
	v_mfma_f32_16x16x32_bf16 v[36:39], v[184:187], v[208:211], v[36:39]
	v_mfma_f32_16x16x32_bf16 v[32:35], v[192:195], v[208:211], v[32:35]
	v_mfma_f32_16x16x32_bf16 v[20:23], v[184:187], v[216:219], v[20:23]
	v_mfma_f32_16x16x32_bf16 v[16:19], v[192:195], v[216:219], v[16:19]
	v_mfma_f32_16x16x32_bf16 v[4:7], v[184:187], v[224:227], v[4:7]
	v_mfma_f32_16x16x32_bf16 v[0:3], v[192:195], v[224:227], v[0:3]
	v_mfma_f32_16x16x32_bf16 v[52:55], v[188:191], v[204:207], v[52:55]
	v_mfma_f32_16x16x32_bf16 v[48:51], v[196:199], v[204:207], v[48:51]
	v_mfma_f32_16x16x32_bf16 v[36:39], v[188:191], v[212:215], v[36:39]
	v_mfma_f32_16x16x32_bf16 v[32:35], v[196:199], v[212:215], v[32:35]
	v_mfma_f32_16x16x32_bf16 v[20:23], v[188:191], v[220:223], v[20:23]
	v_mfma_f32_16x16x32_bf16 v[16:19], v[196:199], v[220:223], v[16:19]
	v_mfma_f32_16x16x32_bf16 v[4:7], v[188:191], v[228:231], v[4:7]
	v_mfma_f32_16x16x32_bf16 v[0:3], v[196:199], v[228:231], v[0:3]
	s_setprio 0
	s_barrier
	s_add_i32 s78, 0, 0x18000
	v_add_u32_e32 v138, s78, v163
	s_add_i32 s79, 0, 0x1c000
	ds_read_b128 v[148:151], v138
	ds_read_b128 v[172:175], v138 offset:1024
	ds_read_b128 v[176:179], v138 offset:2048
	ds_read_b128 v[180:183], v138 offset:3072
	v_add_u32_e32 v138, s79, v163
	ds_read_b128 v[184:187], v138
	ds_read_b128 v[188:191], v138 offset:1024
	ds_read_b128 v[192:195], v138 offset:2048
	ds_read_b128 v[196:199], v138 offset:3072
	s_add_u32 s56, s56, 0x40000
	s_addc_u32 s57, s57, 0
	s_mov_b32 m0, s63
	v_lshl_add_u64 v[238:239], s[56:57], 0, v[128:129]
	ds_read_b128 v[200:203], v166 offset:32768
	ds_read_b128 v[204:207], v166 offset:33792
	ds_read_b128 v[208:211], v166 offset:34816
	ds_read_b128 v[212:215], v166 offset:35840
	ds_read_b128 v[216:219], v166 offset:36864
	ds_read_b128 v[220:223], v166 offset:37888
	ds_read_b128 v[224:227], v166 offset:38912
	ds_read_b128 v[228:231], v166 offset:39936
	global_load_lds_dwordx4 v[238:239], off
	v_lshl_add_u64 v[238:239], s[56:57], 0, v[132:133]
	s_mov_b32 m0, s64
	s_nop 0
	global_load_lds_dwordx4 v[238:239], off
	s_waitcnt vmcnt(8)
	s_waitcnt lgkmcnt(0)
	s_barrier
	s_setprio 1
	s_waitcnt lgkmcnt(0)
	v_mfma_f32_16x16x32_bf16 v[124:127], v[148:151], v[200:203], v[124:127]
	v_mfma_f32_16x16x32_bf16 v[120:123], v[176:179], v[200:203], v[120:123]
	v_mfma_f32_16x16x32_bf16 v[108:111], v[148:151], v[208:211], v[108:111]
	v_mfma_f32_16x16x32_bf16 v[104:107], v[176:179], v[208:211], v[104:107]
	v_mfma_f32_16x16x32_bf16 v[92:95], v[148:151], v[216:219], v[92:95]
	v_mfma_f32_16x16x32_bf16 v[88:91], v[176:179], v[216:219], v[88:91]
	v_mfma_f32_16x16x32_bf16 v[76:79], v[148:151], v[224:227], v[76:79]
	v_mfma_f32_16x16x32_bf16 v[72:75], v[176:179], v[224:227], v[72:75]
	v_mfma_f32_16x16x32_bf16 v[124:127], v[172:175], v[204:207], v[124:127]
	v_mfma_f32_16x16x32_bf16 v[120:123], v[180:183], v[204:207], v[120:123]
	v_mfma_f32_16x16x32_bf16 v[108:111], v[172:175], v[212:215], v[108:111]
	v_mfma_f32_16x16x32_bf16 v[104:107], v[180:183], v[212:215], v[104:107]
	v_mfma_f32_16x16x32_bf16 v[92:95], v[172:175], v[220:223], v[92:95]
	v_mfma_f32_16x16x32_bf16 v[88:91], v[180:183], v[220:223], v[88:91]
	v_mfma_f32_16x16x32_bf16 v[76:79], v[172:175], v[228:231], v[76:79]
	v_mfma_f32_16x16x32_bf16 v[72:75], v[180:183], v[228:231], v[72:75]
	s_setprio 0
	s_setprio 1
	v_mfma_f32_16x16x32_bf16 v[116:119], v[184:187], v[200:203], v[116:119]
	v_mfma_f32_16x16x32_bf16 v[112:115], v[192:195], v[200:203], v[112:115]
	v_mfma_f32_16x16x32_bf16 v[100:103], v[184:187], v[208:211], v[100:103]
	v_mfma_f32_16x16x32_bf16 v[96:99], v[192:195], v[208:211], v[96:99]
	v_mfma_f32_16x16x32_bf16 v[84:87], v[184:187], v[216:219], v[84:87]
	v_mfma_f32_16x16x32_bf16 v[80:83], v[192:195], v[216:219], v[80:83]
	v_mfma_f32_16x16x32_bf16 v[68:71], v[184:187], v[224:227], v[68:71]
	v_mfma_f32_16x16x32_bf16 v[64:67], v[192:195], v[224:227], v[64:67]
	v_mfma_f32_16x16x32_bf16 v[116:119], v[188:191], v[204:207], v[116:119]
	v_mfma_f32_16x16x32_bf16 v[112:115], v[196:199], v[204:207], v[112:115]
	v_mfma_f32_16x16x32_bf16 v[100:103], v[188:191], v[212:215], v[100:103]
	v_mfma_f32_16x16x32_bf16 v[96:99], v[196:199], v[212:215], v[96:99]
	v_mfma_f32_16x16x32_bf16 v[84:87], v[188:191], v[220:223], v[84:87]
	v_mfma_f32_16x16x32_bf16 v[80:83], v[196:199], v[220:223], v[80:83]
	v_mfma_f32_16x16x32_bf16 v[68:71], v[188:191], v[228:231], v[68:71]
	v_mfma_f32_16x16x32_bf16 v[64:67], v[196:199], v[228:231], v[64:67]
	s_setprio 0
	s_barrier
	s_add_i32 s56, s78, s61
	v_lshl_add_u64 v[168:169], v[168:169], 0, s[18:19]
	s_mov_b32 m0, s56
	ds_read_b128 v[200:203], v166 offset:49152
	ds_read_b128 v[204:207], v166 offset:50176
	ds_read_b128 v[208:211], v166 offset:51200
	ds_read_b128 v[212:215], v166 offset:52224
	ds_read_b128 v[216:219], v166 offset:53248
	ds_read_b128 v[220:223], v166 offset:54272
	ds_read_b128 v[224:227], v166 offset:55296
	ds_read_b128 v[228:231], v166 offset:56320
	global_load_lds_dwordx4 v[168:169], off
	s_add_i32 m0, s56, 0x2000
	s_add_u32 s54, s54, 0x40080
	v_lshl_add_u64 v[168:169], v[232:233], 0, s[18:19]
	s_addc_u32 s55, s55, 0
	s_add_i32 s56, s79, s61
	global_load_lds_dwordx4 v[168:169], off
	v_lshl_add_u64 v[168:169], s[54:55], 0, v[130:131]
	s_mov_b32 m0, s56
	s_nop 0
	global_load_lds_dwordx4 v[168:169], off
	v_lshl_add_u64 v[168:169], s[54:55], 0, v[134:135]
	s_add_i32 m0, s56, 0x2000
	s_nop 0
	global_load_lds_dwordx4 v[168:169], off
	v_lshl_add_u64 v[168:169], v[234:235], 0, s[18:19]
	s_mov_b32 m0, s66
	s_nop 0
	global_load_lds_dwordx4 v[168:169], off
	v_lshl_add_u64 v[168:169], v[236:237], 0, s[18:19]
	s_mov_b32 m0, s67
	s_nop 0
	global_load_lds_dwordx4 v[168:169], off
	s_waitcnt vmcnt(8)
	s_waitcnt lgkmcnt(0)
	s_barrier
	s_setprio 1
	s_waitcnt lgkmcnt(0)
	v_mfma_f32_16x16x32_bf16 v[60:63], v[148:151], v[200:203], v[60:63]
	v_mfma_f32_16x16x32_bf16 v[56:59], v[176:179], v[200:203], v[56:59]
	v_mfma_f32_16x16x32_bf16 v[44:47], v[148:151], v[208:211], v[44:47]
	v_mfma_f32_16x16x32_bf16 v[40:43], v[176:179], v[208:211], v[40:43]
	v_mfma_f32_16x16x32_bf16 v[28:31], v[148:151], v[216:219], v[28:31]
	v_mfma_f32_16x16x32_bf16 v[24:27], v[176:179], v[216:219], v[24:27]
	v_mfma_f32_16x16x32_bf16 v[12:15], v[148:151], v[224:227], v[12:15]
	v_mfma_f32_16x16x32_bf16 v[8:11], v[176:179], v[224:227], v[8:11]
	v_mfma_f32_16x16x32_bf16 v[60:63], v[172:175], v[204:207], v[60:63]
	v_mfma_f32_16x16x32_bf16 v[56:59], v[180:183], v[204:207], v[56:59]
	v_mfma_f32_16x16x32_bf16 v[44:47], v[172:175], v[212:215], v[44:47]
	v_mfma_f32_16x16x32_bf16 v[40:43], v[180:183], v[212:215], v[40:43]
	v_mfma_f32_16x16x32_bf16 v[28:31], v[172:175], v[220:223], v[28:31]
	v_mfma_f32_16x16x32_bf16 v[24:27], v[180:183], v[220:223], v[24:27]
	v_mfma_f32_16x16x32_bf16 v[12:15], v[172:175], v[228:231], v[12:15]
	v_mfma_f32_16x16x32_bf16 v[8:11], v[180:183], v[228:231], v[8:11]
	s_setprio 0
	s_setprio 1
	v_mfma_f32_16x16x32_bf16 v[52:55], v[184:187], v[200:203], v[52:55]
	v_mfma_f32_16x16x32_bf16 v[48:51], v[192:195], v[200:203], v[48:51]
	v_mfma_f32_16x16x32_bf16 v[36:39], v[184:187], v[208:211], v[36:39]
	v_mfma_f32_16x16x32_bf16 v[32:35], v[192:195], v[208:211], v[32:35]
	v_mfma_f32_16x16x32_bf16 v[20:23], v[184:187], v[216:219], v[20:23]
	v_mfma_f32_16x16x32_bf16 v[16:19], v[192:195], v[216:219], v[16:19]
	v_mfma_f32_16x16x32_bf16 v[4:7], v[184:187], v[224:227], v[4:7]
	v_mfma_f32_16x16x32_bf16 v[0:3], v[192:195], v[224:227], v[0:3]
	v_mfma_f32_16x16x32_bf16 v[52:55], v[188:191], v[204:207], v[52:55]
	v_mfma_f32_16x16x32_bf16 v[48:51], v[196:199], v[204:207], v[48:51]
	v_mfma_f32_16x16x32_bf16 v[36:39], v[188:191], v[212:215], v[36:39]
	v_mfma_f32_16x16x32_bf16 v[32:35], v[196:199], v[212:215], v[32:35]
	v_mfma_f32_16x16x32_bf16 v[20:23], v[188:191], v[220:223], v[20:23]
	v_mfma_f32_16x16x32_bf16 v[16:19], v[196:199], v[220:223], v[16:19]
	v_mfma_f32_16x16x32_bf16 v[4:7], v[188:191], v[228:231], v[4:7]
	v_mfma_f32_16x16x32_bf16 v[0:3], v[196:199], v[228:231], v[0:3]
	s_setprio 0
	s_add_i32 s77, s77, 2
	s_add_u32 s52, s52, 0x100
	s_addc_u32 s53, s53, 0
	s_add_u32 s75, s75, 0x100
	s_addc_u32 s76, s76, 0
	s_cmp_gt_u32 s77, 13
	s_barrier
	s_cbranch_scc0 .LBB0_1183
	s_and_b64 vcc, exec, s[20:21]
	s_cbranch_vccz .LBB0_1186
	s_barrier

.LBB0_1269:
	ds_read_b128 v[154:157], v150
	ds_read_b128 v[158:161], v150 offset:1024
	ds_read_b128 v[162:165], v150 offset:2048
	ds_read_b128 v[166:169], v150 offset:3072
	ds_read_b128 v[172:175], v151
	ds_read_b128 v[176:179], v151 offset:1024
	ds_read_b128 v[180:183], v151 offset:2048
	ds_read_b128 v[184:187], v151 offset:3072
	s_add_u32 s40, s38, 0xfffc0080
	s_addc_u32 s41, s39, -1
	s_cmp_eq_u32 s69, 12
	s_cselect_b32 s43, s25, s41
	s_cselect_b32 s42, s37, s40
	s_cselect_b32 s41, s23, s68
	s_cselect_b32 s40, s66, s67
	v_lshl_add_u64 v[220:221], s[38:39], 0, v[138:139]
	s_add_i32 m0, s47, 0xc000
	ds_read_b128 v[188:191], v152
	ds_read_b128 v[192:195], v152 offset:1024
	ds_read_b128 v[196:199], v152 offset:2048
	ds_read_b128 v[200:203], v152 offset:3072
	ds_read_b128 v[204:207], v152 offset:4096
	ds_read_b128 v[208:211], v152 offset:5120
	ds_read_b128 v[212:215], v152 offset:6144
	ds_read_b128 v[216:219], v152 offset:7168
	global_load_lds_dwordx4 v[220:221], off
	v_lshl_add_u64 v[220:221], s[38:39], 0, v[140:141]
	s_add_i32 m0, s47, 0xe000
	s_nop 0
	global_load_lds_dwordx4 v[220:221], off
	s_waitcnt vmcnt(8)
	s_waitcnt lgkmcnt(0)
	s_barrier
	s_setprio 1
	s_waitcnt lgkmcnt(0)
	v_mfma_f32_16x16x32_bf16 v[124:127], v[154:157], v[188:191], v[124:127]
	v_mfma_f32_16x16x32_bf16 v[120:123], v[162:165], v[188:191], v[120:123]
	v_mfma_f32_16x16x32_bf16 v[116:119], v[154:157], v[196:199], v[116:119]
	v_mfma_f32_16x16x32_bf16 v[112:115], v[162:165], v[196:199], v[112:115]
	v_mfma_f32_16x16x32_bf16 v[108:111], v[154:157], v[204:207], v[108:111]
	v_mfma_f32_16x16x32_bf16 v[100:103], v[162:165], v[204:207], v[100:103]
	v_mfma_f32_16x16x32_bf16 v[76:79], v[154:157], v[212:215], v[76:79]
	v_mfma_f32_16x16x32_bf16 v[72:75], v[162:165], v[212:215], v[72:75]
	v_mfma_f32_16x16x32_bf16 v[124:127], v[158:161], v[192:195], v[124:127]
	v_mfma_f32_16x16x32_bf16 v[120:123], v[166:169], v[192:195], v[120:123]
	v_mfma_f32_16x16x32_bf16 v[116:119], v[158:161], v[200:203], v[116:119]
	v_mfma_f32_16x16x32_bf16 v[112:115], v[166:169], v[200:203], v[112:115]
	v_mfma_f32_16x16x32_bf16 v[108:111], v[158:161], v[208:211], v[108:111]
	v_mfma_f32_16x16x32_bf16 v[100:103], v[166:169], v[208:211], v[100:103]
	v_mfma_f32_16x16x32_bf16 v[76:79], v[158:161], v[216:219], v[76:79]
	v_mfma_f32_16x16x32_bf16 v[72:75], v[166:169], v[216:219], v[72:75]
	s_setprio 0
	s_setprio 1
	v_mfma_f32_16x16x32_bf16 v[104:107], v[172:175], v[188:191], v[104:107]
	v_mfma_f32_16x16x32_bf16 v[96:99], v[180:183], v[188:191], v[96:99]
	v_mfma_f32_16x16x32_bf16 v[92:95], v[172:175], v[196:199], v[92:95]
	v_mfma_f32_16x16x32_bf16 v[88:91], v[180:183], v[196:199], v[88:91]
	v_mfma_f32_16x16x32_bf16 v[84:87], v[172:175], v[204:207], v[84:87]
	v_mfma_f32_16x16x32_bf16 v[80:83], v[180:183], v[204:207], v[80:83]
	v_mfma_f32_16x16x32_bf16 v[68:71], v[172:175], v[212:215], v[68:71]
	v_mfma_f32_16x16x32_bf16 v[64:67], v[180:183], v[212:215], v[64:67]
	v_mfma_f32_16x16x32_bf16 v[104:107], v[176:179], v[192:195], v[104:107]
	v_mfma_f32_16x16x32_bf16 v[96:99], v[184:187], v[192:195], v[96:99]
	v_mfma_f32_16x16x32_bf16 v[92:95], v[176:179], v[200:203], v[92:95]
	v_mfma_f32_16x16x32_bf16 v[88:91], v[184:187], v[200:203], v[88:91]
	v_mfma_f32_16x16x32_bf16 v[84:87], v[176:179], v[208:211], v[84:87]
	v_mfma_f32_16x16x32_bf16 v[80:83], v[184:187], v[208:211], v[80:83]
	v_mfma_f32_16x16x32_bf16 v[68:71], v[176:179], v[216:219], v[68:71]
	v_mfma_f32_16x16x32_bf16 v[64:67], v[184:187], v[216:219], v[64:67]
	s_setprio 0
	s_barrier
	s_add_i32 s70, s56, s46
	v_lshl_add_u64 v[220:221], s[40:41], 0, v[130:131]
	s_mov_b32 m0, s70
	ds_read_b128 v[188:191], v152 offset:16384
	ds_read_b128 v[192:195], v152 offset:17408
	ds_read_b128 v[196:199], v152 offset:18432
	ds_read_b128 v[200:203], v152 offset:19456
	ds_read_b128 v[204:207], v152 offset:20480
	ds_read_b128 v[208:211], v152 offset:21504
	ds_read_b128 v[212:215], v152 offset:22528
	ds_read_b128 v[216:219], v152 offset:23552
	global_load_lds_dwordx4 v[220:221], off
	s_add_i32 m0, s70, 0x2000
	s_add_u32 s70, s40, 0x40000
	v_lshl_add_u64 v[222:223], s[40:41], 0, v[134:135]
	s_addc_u32 s71, s41, 0
	s_add_i32 s72, s57, s46
	global_load_lds_dwordx4 v[222:223], off
	v_lshl_add_u64 v[224:225], s[70:71], 0, v[130:131]
	s_mov_b32 m0, s72
	v_lshl_add_u64 v[226:227], s[42:43], 0, v[132:133]
	global_load_lds_dwordx4 v[224:225], off
	v_lshl_add_u64 v[224:225], s[70:71], 0, v[134:135]
	s_add_i32 m0, s72, 0x2000
	s_nop 0
	global_load_lds_dwordx4 v[224:225], off
	v_lshl_add_u64 v[224:225], s[42:43], 0, v[128:129]
	s_mov_b32 m0, s47
	s_nop 0
	global_load_lds_dwordx4 v[224:225], off
	s_mov_b32 m0, s48
	s_nop 0
	global_load_lds_dwordx4 v[226:227], off
	s_waitcnt vmcnt(8)
	s_waitcnt lgkmcnt(0)
	s_barrier
	s_setprio 1
	s_waitcnt lgkmcnt(0)
	v_mfma_f32_16x16x32_bf16 v[60:63], v[154:157], v[188:191], v[60:63]
	v_mfma_f32_16x16x32_bf16 v[56:59], v[162:165], v[188:191], v[56:59]
	v_mfma_f32_16x16x32_bf16 v[52:55], v[154:157], v[196:199], v[52:55]
	v_mfma_f32_16x16x32_bf16 v[44:47], v[162:165], v[196:199], v[44:47]
	v_mfma_f32_16x16x32_bf16 v[36:39], v[154:157], v[204:207], v[36:39]
	v_mfma_f32_16x16x32_bf16 v[28:31], v[162:165], v[204:207], v[28:31]
	v_mfma_f32_16x16x32_bf16 v[20:23], v[154:157], v[212:215], v[20:23]
	v_mfma_f32_16x16x32_bf16 v[12:15], v[162:165], v[212:215], v[12:15]
	v_mfma_f32_16x16x32_bf16 v[60:63], v[158:161], v[192:195], v[60:63]
	v_mfma_f32_16x16x32_bf16 v[56:59], v[166:169], v[192:195], v[56:59]
	v_mfma_f32_16x16x32_bf16 v[52:55], v[158:161], v[200:203], v[52:55]
	v_mfma_f32_16x16x32_bf16 v[44:47], v[166:169], v[200:203], v[44:47]
	v_mfma_f32_16x16x32_bf16 v[36:39], v[158:161], v[208:211], v[36:39]
	v_mfma_f32_16x16x32_bf16 v[28:31], v[166:169], v[208:211], v[28:31]
	v_mfma_f32_16x16x32_bf16 v[20:23], v[158:161], v[216:219], v[20:23]
	v_mfma_f32_16x16x32_bf16 v[12:15], v[166:169], v[216:219], v[12:15]
	s_setprio 0
	s_setprio 1
	v_mfma_f32_16x16x32_bf16 v[48:51], v[172:175], v[188:191], v[48:51]
	v_mfma_f32_16x16x32_bf16 v[40:43], v[180:183], v[188:191], v[40:43]
	v_mfma_f32_16x16x32_bf16 v[32:35], v[172:175], v[196:199], v[32:35]
	v_mfma_f32_16x16x32_bf16 v[24:27], v[180:183], v[196:199], v[24:27]
	v_mfma_f32_16x16x32_bf16 v[16:19], v[172:175], v[204:207], v[16:19]
	v_mfma_f32_16x16x32_bf16 v[8:11], v[180:183], v[204:207], v[8:11]
	v_mfma_f32_16x16x32_bf16 v[4:7], v[172:175], v[212:215], v[4:7]
	v_mfma_f32_16x16x32_bf16 v[0:3], v[180:183], v[212:215], v[0:3]
	v_mfma_f32_16x16x32_bf16 v[48:51], v[176:179], v[192:195], v[48:51]
	v_mfma_f32_16x16x32_bf16 v[40:43], v[184:187], v[192:195], v[40:43]
	v_mfma_f32_16x16x32_bf16 v[32:35], v[176:179], v[200:203], v[32:35]
	v_mfma_f32_16x16x32_bf16 v[24:27], v[184:187], v[200:203], v[24:27]
	v_mfma_f32_16x16x32_bf16 v[16:19], v[176:179], v[208:211], v[16:19]
	v_mfma_f32_16x16x32_bf16 v[8:11], v[184:187], v[208:211], v[8:11]
	v_mfma_f32_16x16x32_bf16 v[4:7], v[176:179], v[216:219], v[4:7]
	v_mfma_f32_16x16x32_bf16 v[0:3], v[184:187], v[216:219], v[0:3]
	s_setprio 0
	s_barrier
	s_add_i32 s70, 0, 0x18000
	v_add_u32_e32 v136, s70, v148
	s_add_i32 s71, 0, 0x1c000
	ds_read_b128 v[154:157], v136
	ds_read_b128 v[158:161], v136 offset:1024
	ds_read_b128 v[162:165], v136 offset:2048
	ds_read_b128 v[166:169], v136 offset:3072
	v_add_u32_e32 v136, s71, v148
	ds_read_b128 v[172:175], v136
	ds_read_b128 v[176:179], v136 offset:1024
	ds_read_b128 v[180:183], v136 offset:2048
	ds_read_b128 v[184:187], v136 offset:3072
	s_add_u32 s42, s42, 0x40000
	s_addc_u32 s43, s43, 0
	s_mov_b32 m0, s49
	v_lshl_add_u64 v[228:229], s[42:43], 0, v[128:129]
	ds_read_b128 v[188:191], v152 offset:32768
	ds_read_b128 v[192:195], v152 offset:33792
	ds_read_b128 v[196:199], v152 offset:34816
	ds_read_b128 v[200:203], v152 offset:35840
	ds_read_b128 v[204:207], v152 offset:36864
	ds_read_b128 v[208:211], v152 offset:37888
	ds_read_b128 v[212:215], v152 offset:38912
	ds_read_b128 v[216:219], v152 offset:39936
	global_load_lds_dwordx4 v[228:229], off
	v_lshl_add_u64 v[228:229], s[42:43], 0, v[132:133]
	s_mov_b32 m0, s50
	s_nop 0
	global_load_lds_dwordx4 v[228:229], off
	s_waitcnt vmcnt(8)
	s_waitcnt lgkmcnt(0)
	s_barrier
	s_setprio 1
	s_waitcnt lgkmcnt(0)
	v_mfma_f32_16x16x32_bf16 v[124:127], v[154:157], v[188:191], v[124:127]
	v_mfma_f32_16x16x32_bf16 v[120:123], v[162:165], v[188:191], v[120:123]
	v_mfma_f32_16x16x32_bf16 v[116:119], v[154:157], v[196:199], v[116:119]
	v_mfma_f32_16x16x32_bf16 v[112:115], v[162:165], v[196:199], v[112:115]
	v_mfma_f32_16x16x32_bf16 v[108:111], v[154:157], v[204:207], v[108:111]
	v_mfma_f32_16x16x32_bf16 v[100:103], v[162:165], v[204:207], v[100:103]
	v_mfma_f32_16x16x32_bf16 v[76:79], v[154:157], v[212:215], v[76:79]
	v_mfma_f32_16x16x32_bf16 v[72:75], v[162:165], v[212:215], v[72:75]
	v_mfma_f32_16x16x32_bf16 v[124:127], v[158:161], v[192:195], v[124:127]
	v_mfma_f32_16x16x32_bf16 v[120:123], v[166:169], v[192:195], v[120:123]
	v_mfma_f32_16x16x32_bf16 v[116:119], v[158:161], v[200:203], v[116:119]
	v_mfma_f32_16x16x32_bf16 v[112:115], v[166:169], v[200:203], v[112:115]
	v_mfma_f32_16x16x32_bf16 v[108:111], v[158:161], v[208:211], v[108:111]
	v_mfma_f32_16x16x32_bf16 v[100:103], v[166:169], v[208:211], v[100:103]
	v_mfma_f32_16x16x32_bf16 v[76:79], v[158:161], v[216:219], v[76:79]
	v_mfma_f32_16x16x32_bf16 v[72:75], v[166:169], v[216:219], v[72:75]
	s_setprio 0
	s_setprio 1
	v_mfma_f32_16x16x32_bf16 v[104:107], v[172:175], v[188:191], v[104:107]
	v_mfma_f32_16x16x32_bf16 v[96:99], v[180:183], v[188:191], v[96:99]
	v_mfma_f32_16x16x32_bf16 v[92:95], v[172:175], v[196:199], v[92:95]
	v_mfma_f32_16x16x32_bf16 v[88:91], v[180:183], v[196:199], v[88:91]
	v_mfma_f32_16x16x32_bf16 v[84:87], v[172:175], v[204:207], v[84:87]
	v_mfma_f32_16x16x32_bf16 v[80:83], v[180:183], v[204:207], v[80:83]
	v_mfma_f32_16x16x32_bf16 v[68:71], v[172:175], v[212:215], v[68:71]
	v_mfma_f32_16x16x32_bf16 v[64:67], v[180:183], v[212:215], v[64:67]
	v_mfma_f32_16x16x32_bf16 v[104:107], v[176:179], v[192:195], v[104:107]
	v_mfma_f32_16x16x32_bf16 v[96:99], v[184:187], v[192:195], v[96:99]
	v_mfma_f32_16x16x32_bf16 v[92:95], v[176:179], v[200:203], v[92:95]
	v_mfma_f32_16x16x32_bf16 v[88:91], v[184:187], v[200:203], v[88:91]
	v_mfma_f32_16x16x32_bf16 v[84:87], v[176:179], v[208:211], v[84:87]
	v_mfma_f32_16x16x32_bf16 v[80:83], v[184:187], v[208:211], v[80:83]
	v_mfma_f32_16x16x32_bf16 v[68:71], v[176:179], v[216:219], v[68:71]
	v_mfma_f32_16x16x32_bf16 v[64:67], v[184:187], v[216:219], v[64:67]
	s_setprio 0
	s_barrier
	s_add_i32 s42, s70, s46
	v_lshl_add_u64 v[220:221], v[220:221], 0, s[12:13]
	s_mov_b32 m0, s42
	ds_read_b128 v[188:191], v152 offset:49152
	ds_read_b128 v[192:195], v152 offset:50176
	ds_read_b128 v[196:199], v152 offset:51200
	ds_read_b128 v[200:203], v152 offset:52224
	ds_read_b128 v[204:207], v152 offset:53248
	ds_read_b128 v[208:211], v152 offset:54272
	ds_read_b128 v[212:215], v152 offset:55296
	ds_read_b128 v[216:219], v152 offset:56320
	global_load_lds_dwordx4 v[220:221], off
	s_add_i32 m0, s42, 0x2000
	s_add_u32 s40, s40, 0x40080
	v_lshl_add_u64 v[220:221], v[222:223], 0, s[12:13]
	s_addc_u32 s41, s41, 0
	s_add_i32 s42, s71, s46
	global_load_lds_dwordx4 v[220:221], off
	v_lshl_add_u64 v[220:221], s[40:41], 0, v[130:131]
	s_mov_b32 m0, s42
	s_nop 0
	global_load_lds_dwordx4 v[220:221], off
	v_lshl_add_u64 v[220:221], s[40:41], 0, v[134:135]
	s_add_i32 m0, s42, 0x2000
	s_nop 0
	global_load_lds_dwordx4 v[220:221], off
	v_lshl_add_u64 v[220:221], v[224:225], 0, s[12:13]
	s_mov_b32 m0, s52
	s_nop 0
	global_load_lds_dwordx4 v[220:221], off
	v_lshl_add_u64 v[220:221], v[226:227], 0, s[12:13]
	s_mov_b32 m0, s53
	s_nop 0
	global_load_lds_dwordx4 v[220:221], off
	s_waitcnt vmcnt(8)
	s_waitcnt lgkmcnt(0)
	s_barrier
	s_setprio 1
	s_waitcnt lgkmcnt(0)
	v_mfma_f32_16x16x32_bf16 v[60:63], v[154:157], v[188:191], v[60:63]
	v_mfma_f32_16x16x32_bf16 v[56:59], v[162:165], v[188:191], v[56:59]
	v_mfma_f32_16x16x32_bf16 v[52:55], v[154:157], v[196:199], v[52:55]
	v_mfma_f32_16x16x32_bf16 v[44:47], v[162:165], v[196:199], v[44:47]
	v_mfma_f32_16x16x32_bf16 v[36:39], v[154:157], v[204:207], v[36:39]
	v_mfma_f32_16x16x32_bf16 v[28:31], v[162:165], v[204:207], v[28:31]
	v_mfma_f32_16x16x32_bf16 v[20:23], v[154:157], v[212:215], v[20:23]
	v_mfma_f32_16x16x32_bf16 v[12:15], v[162:165], v[212:215], v[12:15]
	v_mfma_f32_16x16x32_bf16 v[60:63], v[158:161], v[192:195], v[60:63]
	v_mfma_f32_16x16x32_bf16 v[56:59], v[166:169], v[192:195], v[56:59]
	v_mfma_f32_16x16x32_bf16 v[52:55], v[158:161], v[200:203], v[52:55]
	v_mfma_f32_16x16x32_bf16 v[44:47], v[166:169], v[200:203], v[44:47]
	v_mfma_f32_16x16x32_bf16 v[36:39], v[158:161], v[208:211], v[36:39]
	v_mfma_f32_16x16x32_bf16 v[28:31], v[166:169], v[208:211], v[28:31]
	v_mfma_f32_16x16x32_bf16 v[20:23], v[158:161], v[216:219], v[20:23]
	v_mfma_f32_16x16x32_bf16 v[12:15], v[166:169], v[216:219], v[12:15]
	s_setprio 0
	s_setprio 1
	v_mfma_f32_16x16x32_bf16 v[48:51], v[172:175], v[188:191], v[48:51]
	v_mfma_f32_16x16x32_bf16 v[40:43], v[180:183], v[188:191], v[40:43]
	v_mfma_f32_16x16x32_bf16 v[32:35], v[172:175], v[196:199], v[32:35]
	v_mfma_f32_16x16x32_bf16 v[24:27], v[180:183], v[196:199], v[24:27]
	v_mfma_f32_16x16x32_bf16 v[16:19], v[172:175], v[204:207], v[16:19]
	v_mfma_f32_16x16x32_bf16 v[8:11], v[180:183], v[204:207], v[8:11]
	v_mfma_f32_16x16x32_bf16 v[4:7], v[172:175], v[212:215], v[4:7]
	v_mfma_f32_16x16x32_bf16 v[0:3], v[180:183], v[212:215], v[0:3]
	v_mfma_f32_16x16x32_bf16 v[48:51], v[176:179], v[192:195], v[48:51]
	v_mfma_f32_16x16x32_bf16 v[40:43], v[184:187], v[192:195], v[40:43]
	v_mfma_f32_16x16x32_bf16 v[32:35], v[176:179], v[200:203], v[32:35]
	v_mfma_f32_16x16x32_bf16 v[24:27], v[184:187], v[200:203], v[24:27]
	v_mfma_f32_16x16x32_bf16 v[16:19], v[176:179], v[208:211], v[16:19]
	v_mfma_f32_16x16x32_bf16 v[8:11], v[184:187], v[208:211], v[8:11]
	v_mfma_f32_16x16x32_bf16 v[4:7], v[176:179], v[216:219], v[4:7]
	v_mfma_f32_16x16x32_bf16 v[0:3], v[184:187], v[216:219], v[0:3]
	s_setprio 0
	s_add_i32 s69, s69, 2
	s_add_u32 s38, s38, 0x100
	s_addc_u32 s39, s39, 0
	s_add_u32 s67, s67, 0x100
	s_addc_u32 s68, s68, 0
	s_cmp_gt_u32 s69, 13
	s_barrier
	s_cbranch_scc0 .LBB0_1269
	s_and_b64 vcc, exec, s[14:15]
	s_cbranch_vccz .LBB0_1272
	s_barrier
